# lora GEMM decay epilogue: the bias vectors are loaded once per tile and copied at the old load sites, removing the per-row-group vmcnt(0) that also waited on stores
# speedup vs baseline: 1.0090x; 1.0028x over previous
.LBB0_800:
	v_cmp_gt_i32_e32 vcc, s36, v152
	v_ashrrev_i32_e32 v155, 31, v154
	v_ashrrev_i32_e32 v153, 31, v152
	s_and_saveexec_b64 s[34:35], vcc
	s_cbranch_execz .LBB0_808
	v_readlane_b32 s68, v239, 33
	v_lshlrev_b64 v[156:157], 2, v[154:155]
	v_readlane_b32 s70, v239, 35
	v_readlane_b32 s71, v239, 36
	v_readlane_b32 s69, v239, 34
	v_readlane_b32 s72, v239, 37
	v_lshl_add_u64 v[158:159], s[70:71], 0, v[156:157]
	global_load_dwordx4 v[172:175], v[158:159], off
	global_load_dwordx4 v[176:179], v[158:159], off offset:16
	global_load_dwordx4 v[180:183], v[158:159], off offset:512
	global_load_dwordx4 v[184:187], v[158:159], off offset:528
	s_waitcnt vmcnt(0)
	s_nop 1
	v_mov_b64_e32 v[128:129], v[176:177]
	v_mov_b64_e32 v[130:131], v[178:179]
	s_nop 1
	v_mov_b64_e32 v[132:133], v[172:173]
	v_mov_b64_e32 v[134:135], v[174:175]
	v_readlane_b32 s73, v239, 38
	v_readlane_b32 s74, v239, 39
	v_readlane_b32 s75, v239, 40
	v_readlane_b32 s76, v239, 41
	v_readlane_b32 s77, v239, 42
	v_readlane_b32 s78, v239, 43
	v_readlane_b32 s79, v239, 44
	v_readlane_b32 s80, v239, 45
	v_readlane_b32 s81, v239, 46
	v_readlane_b32 s82, v239, 47
	v_readlane_b32 s83, v239, 48
	v_add_f32_e32 v120, v120, v128
	v_add_f32_e32 v124, v124, v132
	v_min_f32_e32 v128, 0, v124
	v_mul_f32_e64 v124, |v124|, s49
	v_exp_f32_e32 v124, v124
	v_add_f32_e32 v125, v125, v133
	v_add_f32_e32 v121, v121, v129
	v_add_f32_e32 v126, v126, v134
	v_add_f32_e32 v124, 1.0, v124
	v_cmp_gt_f32_e32 vcc, s90, v124
	v_add_f32_e32 v122, v122, v130
	v_add_f32_e32 v127, v127, v135
	v_cndmask_b32_e64 v132, 0, 32, vcc
	v_ldexp_f32 v124, v124, v132
	v_log_f32_e32 v124, v124
	v_add_f32_e32 v123, v123, v131
	v_mul_f32_e32 v132, 0x3f317217, v124
	v_fma_f32 v132, v124, s91, -v132
	v_fmac_f32_e32 v132, 0x3377d1cf, v124
	v_fmac_f32_e32 v132, 0x3f317217, v124
	v_cmp_lt_f32_e64 s[0:1], |v124|, s96
	s_nop 1
	v_cndmask_b32_e64 v124, v124, v132, s[0:1]
	v_cndmask_b32_e32 v132, 0, v167, vcc
	v_sub_f32_e32 v124, v124, v132
	v_sub_f32_e32 v124, v128, v124
	v_min_f32_e32 v128, 0, v120
	v_mul_f32_e64 v120, |v120|, s49
	v_exp_f32_e32 v120, v120
	v_add_f32_e32 v124, -0.5, v124
	v_mul_f32_e32 v124, 0x3fb8aa3b, v124
	v_exp_f32_e32 v124, v124
	v_add_f32_e32 v120, 1.0, v120
	v_cmp_gt_f32_e32 vcc, s90, v120
	v_mul_f32_e32 v124, 0xbfb8aa3b, v124
	s_nop 0
	v_cndmask_b32_e64 v132, 0, 32, vcc
	v_ldexp_f32 v120, v120, v132
	v_log_f32_e32 v120, v120
	v_exp_f32_e32 v124, v124
	v_mul_f32_e32 v132, 0x3f317217, v120
	v_fma_f32 v132, v120, s91, -v132
	v_fmac_f32_e32 v132, 0x3377d1cf, v120
	v_fmac_f32_e32 v132, 0x3f317217, v120
	v_cmp_lt_f32_e64 s[0:1], |v120|, s96
	s_nop 1
	v_cndmask_b32_e64 v120, v120, v132, s[0:1]
	v_cndmask_b32_e32 v132, 0, v167, vcc
	v_sub_f32_e32 v120, v120, v132
	v_sub_f32_e32 v120, v128, v120
	v_min_f32_e32 v128, 0, v125
	v_mul_f32_e64 v125, |v125|, s49
	v_exp_f32_e32 v125, v125
	v_add_f32_e32 v120, -0.5, v120
	v_mul_f32_e32 v120, 0x3fb8aa3b, v120
	v_exp_f32_e32 v120, v120
	v_add_f32_e32 v125, 1.0, v125
	v_cmp_gt_f32_e32 vcc, s90, v125
	v_mul_f32_e32 v120, 0xbfb8aa3b, v120
	s_nop 0
	v_cndmask_b32_e64 v129, 0, 32, vcc
	v_ldexp_f32 v125, v125, v129
	v_log_f32_e32 v125, v125
	v_exp_f32_e32 v120, v120
	v_mul_f32_e32 v129, 0x3f317217, v125
	v_fma_f32 v129, v125, s91, -v129
	v_fmac_f32_e32 v129, 0x3377d1cf, v125
	v_fmac_f32_e32 v129, 0x3f317217, v125
	v_cmp_lt_f32_e64 s[0:1], |v125|, s96
	s_nop 1
	v_cndmask_b32_e64 v125, v125, v129, s[0:1]
	v_cndmask_b32_e32 v129, 0, v167, vcc
	v_sub_f32_e32 v125, v125, v129
	v_sub_f32_e32 v125, v128, v125
	v_min_f32_e32 v128, 0, v121
	v_mul_f32_e64 v121, |v121|, s49
	v_exp_f32_e32 v121, v121
	v_add_f32_e32 v125, -0.5, v125
	v_mul_f32_e32 v125, 0x3fb8aa3b, v125
	v_exp_f32_e32 v125, v125
	v_add_f32_e32 v121, 1.0, v121
	v_cmp_gt_f32_e32 vcc, s90, v121
	v_mul_f32_e32 v125, 0xbfb8aa3b, v125
	s_nop 0
	v_cndmask_b32_e64 v129, 0, 32, vcc
	v_ldexp_f32 v121, v121, v129
	v_log_f32_e32 v121, v121
	v_exp_f32_e32 v125, v125
	v_mul_f32_e32 v129, 0x3f317217, v121
	v_fma_f32 v129, v121, s91, -v129
	v_fmac_f32_e32 v129, 0x3377d1cf, v121
	v_fmac_f32_e32 v129, 0x3f317217, v121
	v_cmp_lt_f32_e64 s[0:1], |v121|, s96
	s_nop 1
	v_cndmask_b32_e64 v121, v121, v129, s[0:1]
	v_cndmask_b32_e32 v129, 0, v167, vcc
	v_sub_f32_e32 v121, v121, v129
	v_sub_f32_e32 v121, v128, v121
	v_min_f32_e32 v128, 0, v126
	v_mul_f32_e64 v126, |v126|, s49
	v_exp_f32_e32 v126, v126
	v_add_f32_e32 v121, -0.5, v121
	v_mul_f32_e32 v121, 0x3fb8aa3b, v121
	v_exp_f32_e32 v121, v121
	v_add_f32_e32 v126, 1.0, v126
	v_cmp_gt_f32_e32 vcc, s90, v126
	v_mul_f32_e32 v121, 0xbfb8aa3b, v121
	s_nop 0
	v_cndmask_b32_e64 v129, 0, 32, vcc
	v_ldexp_f32 v126, v126, v129
	v_log_f32_e32 v126, v126
	v_exp_f32_e32 v121, v121
	v_mul_f32_e32 v129, 0x3f317217, v126
	v_fma_f32 v129, v126, s91, -v129
	v_fmac_f32_e32 v129, 0x3377d1cf, v126
	v_fmac_f32_e32 v129, 0x3f317217, v126
	v_cmp_lt_f32_e64 s[0:1], |v126|, s96
	s_nop 1
	v_cndmask_b32_e64 v126, v126, v129, s[0:1]
	v_cndmask_b32_e32 v129, 0, v167, vcc
	v_sub_f32_e32 v126, v126, v129
	v_sub_f32_e32 v126, v128, v126
	v_min_f32_e32 v128, 0, v122
	v_mul_f32_e64 v122, |v122|, s49
	v_exp_f32_e32 v122, v122
	v_add_f32_e32 v126, -0.5, v126
	v_mul_f32_e32 v126, 0x3fb8aa3b, v126
	v_exp_f32_e32 v126, v126
	v_add_f32_e32 v122, 1.0, v122
	v_cmp_gt_f32_e32 vcc, s90, v122
	v_mul_f32_e32 v126, 0xbfb8aa3b, v126
	s_nop 0
	v_cndmask_b32_e64 v129, 0, 32, vcc
	v_ldexp_f32 v122, v122, v129
	v_log_f32_e32 v122, v122
	v_exp_f32_e32 v126, v126
	v_mul_f32_e32 v129, 0x3f317217, v122
	v_fma_f32 v129, v122, s91, -v129
	v_fmac_f32_e32 v129, 0x3377d1cf, v122
	v_fmac_f32_e32 v129, 0x3f317217, v122
	v_cmp_lt_f32_e64 s[0:1], |v122|, s96
	s_nop 1
	v_cndmask_b32_e64 v122, v122, v129, s[0:1]
	v_cndmask_b32_e32 v129, 0, v167, vcc
	v_sub_f32_e32 v122, v122, v129
	v_sub_f32_e32 v122, v128, v122
	v_min_f32_e32 v128, 0, v127
	v_mul_f32_e64 v127, |v127|, s49
	v_exp_f32_e32 v127, v127
	v_add_f32_e32 v122, -0.5, v122
	v_mul_f32_e32 v122, 0x3fb8aa3b, v122
	v_exp_f32_e32 v122, v122
	v_add_f32_e32 v127, 1.0, v127
	v_cmp_gt_f32_e32 vcc, s90, v127
	v_mul_f32_e32 v122, 0xbfb8aa3b, v122
	s_nop 0
	v_cndmask_b32_e64 v129, 0, 32, vcc
	v_ldexp_f32 v127, v127, v129
	v_log_f32_e32 v127, v127
	v_exp_f32_e32 v122, v122
	v_mul_f32_e32 v129, 0x3f317217, v127
	v_fma_f32 v129, v127, s91, -v129
	v_fmac_f32_e32 v129, 0x3377d1cf, v127
	v_fmac_f32_e32 v129, 0x3f317217, v127
	v_cmp_lt_f32_e64 s[0:1], |v127|, s96
	s_nop 1
	v_cndmask_b32_e64 v127, v127, v129, s[0:1]
	v_cndmask_b32_e32 v129, 0, v167, vcc
	v_sub_f32_e32 v127, v127, v129
	v_sub_f32_e32 v127, v128, v127
	v_min_f32_e32 v128, 0, v123
	v_mul_f32_e64 v123, |v123|, s49
	v_exp_f32_e32 v123, v123
	v_add_f32_e32 v127, -0.5, v127
	v_mul_f32_e32 v127, 0x3fb8aa3b, v127
	v_exp_f32_e32 v127, v127
	v_add_f32_e32 v123, 1.0, v123
	v_cmp_gt_f32_e32 vcc, s90, v123
	v_mul_f32_e32 v127, 0xbfb8aa3b, v127
	s_nop 0
	v_cndmask_b32_e64 v129, 0, 32, vcc
	v_ldexp_f32 v123, v123, v129
	v_log_f32_e32 v123, v123
	v_exp_f32_e32 v127, v127
	v_mul_f32_e32 v129, 0x3f317217, v123
	v_fma_f32 v129, v123, s91, -v129
	v_fmac_f32_e32 v129, 0x3377d1cf, v123
	v_fmac_f32_e32 v129, 0x3f317217, v123
	v_cmp_lt_f32_e64 s[0:1], |v123|, s96
	s_nop 1
	v_cndmask_b32_e64 v123, v123, v129, s[0:1]
	v_cndmask_b32_e32 v129, 0, v167, vcc
	v_sub_f32_e32 v123, v123, v129
	v_sub_f32_e32 v123, v128, v123
	v_add_f32_e32 v123, -0.5, v123
	v_mul_f32_e32 v123, 0x3fb8aa3b, v123
	v_exp_f32_e32 v123, v123
	v_lshlrev_b64 v[128:129], 12, v[152:153]
	v_lshl_add_u64 v[128:129], s[10:11], 0, v[128:129]
	v_lshl_add_u64 v[128:129], v[128:129], 0, v[156:157]
	v_mul_f32_e32 v123, 0xbfb8aa3b, v123
	v_exp_f32_e32 v123, v123
	global_store_dwordx4 v[128:129], v[124:127], off
	global_store_dwordx4 v[128:129], v[120:123], off offset:16
	s_nop 1
	v_mov_b64_e32 v[120:121], v[184:185]
	v_mov_b64_e32 v[122:123], v[186:187]
	s_nop 0
	s_nop 1
	v_mov_b64_e32 v[124:125], v[180:181]
	v_mov_b64_e32 v[126:127], v[182:183]
	v_add_f32_e32 v112, v112, v120
	v_add_f32_e32 v116, v116, v124
	v_min_f32_e32 v120, 0, v116
	v_mul_f32_e64 v116, |v116|, s49
	v_exp_f32_e32 v116, v116
	v_add_f32_e32 v117, v117, v125
	v_add_f32_e32 v113, v113, v121
	v_add_f32_e32 v118, v118, v126
	v_add_f32_e32 v116, 1.0, v116
	v_cmp_gt_f32_e32 vcc, s90, v116
	v_add_f32_e32 v114, v114, v122
	v_add_f32_e32 v119, v119, v127
	v_cndmask_b32_e64 v124, 0, 32, vcc
	v_ldexp_f32 v116, v116, v124
	v_log_f32_e32 v116, v116
	v_add_f32_e32 v115, v115, v123
	v_mul_f32_e32 v124, 0x3f317217, v116
	v_fma_f32 v124, v116, s91, -v124
	v_fmac_f32_e32 v124, 0x3377d1cf, v116
	v_fmac_f32_e32 v124, 0x3f317217, v116
	v_cmp_lt_f32_e64 s[0:1], |v116|, s96
	s_nop 1
	v_cndmask_b32_e64 v116, v116, v124, s[0:1]
	v_cndmask_b32_e32 v124, 0, v167, vcc
	v_sub_f32_e32 v116, v116, v124
	v_sub_f32_e32 v116, v120, v116
	v_min_f32_e32 v120, 0, v112
	v_mul_f32_e64 v112, |v112|, s49
	v_exp_f32_e32 v112, v112
	v_add_f32_e32 v116, -0.5, v116
	v_add_f32_e32 v112, 1.0, v112
	v_cmp_gt_f32_e32 vcc, s90, v112
	s_nop 1
	v_cndmask_b32_e64 v124, 0, 32, vcc
	v_ldexp_f32 v112, v112, v124
	v_log_f32_e32 v112, v112
	s_nop 0
	v_mul_f32_e32 v124, 0x3f317217, v112
	v_fma_f32 v124, v112, s91, -v124
	v_fmac_f32_e32 v124, 0x3377d1cf, v112
	v_fmac_f32_e32 v124, 0x3f317217, v112
	v_cmp_lt_f32_e64 s[0:1], |v112|, s96
	s_nop 1
	v_cndmask_b32_e64 v112, v112, v124, s[0:1]
	v_cndmask_b32_e32 v124, 0, v167, vcc
	v_sub_f32_e32 v112, v112, v124
	v_sub_f32_e32 v112, v120, v112
	v_add_f32_e32 v120, -0.5, v112
	v_mul_f32_e32 v112, 0x3fb8aa3b, v116
	v_mul_f32_e32 v116, 0x3fb8aa3b, v120
	v_min_f32_e32 v120, 0, v117
	v_mul_f32_e64 v117, |v117|, s49
	v_exp_f32_e32 v117, v117
	v_exp_f32_e32 v112, v112
	v_exp_f32_e32 v116, v116
	v_add_f32_e32 v117, 1.0, v117
	v_cmp_gt_f32_e32 vcc, s90, v117
	v_mul_f32_e32 v112, 0xbfb8aa3b, v112
	v_exp_f32_e32 v112, v112
	v_cndmask_b32_e64 v121, 0, 32, vcc
	v_ldexp_f32 v117, v117, v121
	v_log_f32_e32 v117, v117
	v_mul_f32_e32 v116, 0xbfb8aa3b, v116
	v_exp_f32_e32 v116, v116
	v_mul_f32_e32 v121, 0x3f317217, v117
	v_fma_f32 v121, v117, s91, -v121
	v_fmac_f32_e32 v121, 0x3377d1cf, v117
	v_fmac_f32_e32 v121, 0x3f317217, v117
	v_cmp_lt_f32_e64 s[0:1], |v117|, s96
	s_nop 1
	v_cndmask_b32_e64 v117, v117, v121, s[0:1]
	v_cndmask_b32_e32 v121, 0, v167, vcc
	v_sub_f32_e32 v117, v117, v121
	v_sub_f32_e32 v117, v120, v117
	v_min_f32_e32 v120, 0, v113
	v_mul_f32_e64 v113, |v113|, s49
	v_exp_f32_e32 v113, v113
	v_add_f32_e32 v117, -0.5, v117
	v_add_f32_e32 v113, 1.0, v113
	v_cmp_gt_f32_e32 vcc, s90, v113
	s_nop 1
	v_cndmask_b32_e64 v121, 0, 32, vcc
	v_ldexp_f32 v113, v113, v121
	v_log_f32_e32 v113, v113
	s_nop 0
	v_mul_f32_e32 v121, 0x3f317217, v113
	v_fma_f32 v121, v113, s91, -v121
	v_fmac_f32_e32 v121, 0x3377d1cf, v113
	v_fmac_f32_e32 v121, 0x3f317217, v113
	v_cmp_lt_f32_e64 s[0:1], |v113|, s96
	s_nop 1
	v_cndmask_b32_e64 v113, v113, v121, s[0:1]
	v_cndmask_b32_e32 v121, 0, v167, vcc
	v_sub_f32_e32 v113, v113, v121
	v_sub_f32_e32 v113, v120, v113
	v_add_f32_e32 v120, -0.5, v113
	v_mul_f32_e32 v113, 0x3fb8aa3b, v117
	v_mul_f32_e32 v117, 0x3fb8aa3b, v120
	v_min_f32_e32 v120, 0, v118
	v_mul_f32_e64 v118, |v118|, s49
	v_exp_f32_e32 v118, v118
	v_exp_f32_e32 v113, v113
	v_exp_f32_e32 v117, v117
	v_add_f32_e32 v118, 1.0, v118
	v_cmp_gt_f32_e32 vcc, s90, v118
	v_mul_f32_e32 v113, 0xbfb8aa3b, v113
	v_exp_f32_e32 v113, v113
	v_cndmask_b32_e64 v121, 0, 32, vcc
	v_ldexp_f32 v118, v118, v121
	v_log_f32_e32 v118, v118
	v_mul_f32_e32 v117, 0xbfb8aa3b, v117
	v_exp_f32_e32 v117, v117
	v_mul_f32_e32 v121, 0x3f317217, v118
	v_fma_f32 v121, v118, s91, -v121
	v_fmac_f32_e32 v121, 0x3377d1cf, v118
	v_fmac_f32_e32 v121, 0x3f317217, v118
	v_cmp_lt_f32_e64 s[0:1], |v118|, s96
	s_nop 1
	v_cndmask_b32_e64 v118, v118, v121, s[0:1]
	v_cndmask_b32_e32 v121, 0, v167, vcc
	v_sub_f32_e32 v118, v118, v121
	v_sub_f32_e32 v118, v120, v118
	v_min_f32_e32 v120, 0, v114
	v_mul_f32_e64 v114, |v114|, s49
	v_exp_f32_e32 v114, v114
	v_add_f32_e32 v118, -0.5, v118
	v_add_f32_e32 v114, 1.0, v114
	v_cmp_gt_f32_e32 vcc, s90, v114
	s_nop 1
	v_cndmask_b32_e64 v121, 0, 32, vcc
	v_ldexp_f32 v114, v114, v121
	v_log_f32_e32 v114, v114
	s_nop 0
	v_mul_f32_e32 v121, 0x3f317217, v114
	v_fma_f32 v121, v114, s91, -v121
	v_fmac_f32_e32 v121, 0x3377d1cf, v114
	v_fmac_f32_e32 v121, 0x3f317217, v114
	v_cmp_lt_f32_e64 s[0:1], |v114|, s96
	s_nop 1
	v_cndmask_b32_e64 v114, v114, v121, s[0:1]
	v_cndmask_b32_e32 v121, 0, v167, vcc
	v_sub_f32_e32 v114, v114, v121
	v_sub_f32_e32 v114, v120, v114
	v_add_f32_e32 v120, -0.5, v114
	v_mul_f32_e32 v114, 0x3fb8aa3b, v118
	v_mul_f32_e32 v118, 0x3fb8aa3b, v120
	v_min_f32_e32 v120, 0, v119
	v_mul_f32_e64 v119, |v119|, s49
	v_exp_f32_e32 v119, v119
	v_exp_f32_e32 v114, v114
	v_exp_f32_e32 v118, v118
	v_add_f32_e32 v119, 1.0, v119
	v_cmp_gt_f32_e32 vcc, s90, v119
	v_mul_f32_e32 v114, 0xbfb8aa3b, v114
	v_exp_f32_e32 v114, v114
	v_cndmask_b32_e64 v121, 0, 32, vcc
	v_ldexp_f32 v119, v119, v121
	v_log_f32_e32 v119, v119
	v_mul_f32_e32 v118, 0xbfb8aa3b, v118
	v_exp_f32_e32 v118, v118
	v_mul_f32_e32 v121, 0x3f317217, v119
	v_fma_f32 v121, v119, s91, -v121
	v_fmac_f32_e32 v121, 0x3377d1cf, v119
	v_fmac_f32_e32 v121, 0x3f317217, v119
	v_cmp_lt_f32_e64 s[0:1], |v119|, s96
	s_nop 1
	v_cndmask_b32_e64 v119, v119, v121, s[0:1]
	v_cndmask_b32_e32 v121, 0, v167, vcc
	v_sub_f32_e32 v119, v119, v121
	v_sub_f32_e32 v119, v120, v119
	v_min_f32_e32 v120, 0, v115
	v_mul_f32_e64 v115, |v115|, s49
	v_exp_f32_e32 v115, v115
	v_add_f32_e32 v119, -0.5, v119
	v_add_f32_e32 v115, 1.0, v115
	v_cmp_gt_f32_e32 vcc, s90, v115
	s_nop 1
	v_cndmask_b32_e64 v121, 0, 32, vcc
	v_ldexp_f32 v115, v115, v121
	v_log_f32_e32 v115, v115
	s_nop 0
	v_mul_f32_e32 v121, 0x3f317217, v115
	v_fma_f32 v121, v115, s91, -v121
	v_fmac_f32_e32 v121, 0x3377d1cf, v115
	v_fmac_f32_e32 v121, 0x3f317217, v115
	v_cmp_lt_f32_e64 s[0:1], |v115|, s96
	s_nop 1
	v_cndmask_b32_e64 v115, v115, v121, s[0:1]
	v_cndmask_b32_e32 v121, 0, v167, vcc
	v_sub_f32_e32 v115, v115, v121
	v_sub_f32_e32 v115, v120, v115
	v_add_f32_e32 v120, -0.5, v115
	v_mul_f32_e32 v115, 0x3fb8aa3b, v119
	v_exp_f32_e32 v115, v115
	v_mul_f32_e32 v119, 0x3fb8aa3b, v120
	v_exp_f32_e32 v119, v119
	v_mul_f32_e32 v115, 0xbfb8aa3b, v115
	v_exp_f32_e32 v115, v115
	v_mul_f32_e32 v119, 0xbfb8aa3b, v119
	v_exp_f32_e32 v119, v119
	global_store_dwordx4 v[128:129], v[112:115], off offset:512
	global_store_dwordx4 v[128:129], v[116:119], off offset:528
	s_or_b64 exec, exec, s[34:35]
	v_cmp_gt_i32_e32 vcc, s37, v152
	s_and_saveexec_b64 s[34:35], vcc
	s_cbranch_execnz .LBB0_809

.LBB0_803:
	v_readlane_b32 s68, v239, 33
	v_lshlrev_b64 v[106:107], 2, v[154:155]
	v_readlane_b32 s70, v239, 35
	v_readlane_b32 s71, v239, 36
	v_or_b32_e32 v104, 32, v152
	v_ashrrev_i32_e32 v105, 31, v104
	v_lshl_add_u64 v[108:109], s[70:71], 0, v[106:107]
	s_nop 1
	v_mov_b64_e32 v[96:97], v[176:177]
	v_mov_b64_e32 v[98:99], v[178:179]
	s_nop 1
	v_mov_b64_e32 v[100:101], v[172:173]
	v_mov_b64_e32 v[102:103], v[174:175]
	v_readlane_b32 s69, v239, 34
	v_readlane_b32 s72, v239, 37
	v_readlane_b32 s73, v239, 38
	v_readlane_b32 s74, v239, 39
	v_readlane_b32 s75, v239, 40
	v_readlane_b32 s76, v239, 41
	v_readlane_b32 s77, v239, 42
	v_readlane_b32 s78, v239, 43
	v_readlane_b32 s79, v239, 44
	v_readlane_b32 s80, v239, 45
	v_readlane_b32 s81, v239, 46
	v_readlane_b32 s82, v239, 47
	v_readlane_b32 s83, v239, 48
	v_add_f32_e32 v88, v88, v96
	v_add_f32_e32 v92, v92, v100
	v_min_f32_e32 v96, 0, v92
	v_mul_f32_e64 v92, |v92|, s49
	v_exp_f32_e32 v92, v92
	v_add_f32_e32 v93, v93, v101
	v_add_f32_e32 v89, v89, v97
	v_add_f32_e32 v94, v94, v102
	v_add_f32_e32 v92, 1.0, v92
	v_cmp_gt_f32_e32 vcc, s90, v92
	v_add_f32_e32 v90, v90, v98
	v_add_f32_e32 v95, v95, v103
	v_cndmask_b32_e64 v100, 0, 32, vcc
	v_ldexp_f32 v92, v92, v100
	v_log_f32_e32 v92, v92
	v_add_f32_e32 v91, v91, v99
	v_mul_f32_e32 v100, 0x3f317217, v92
	v_fma_f32 v100, v92, s91, -v100
	v_fmac_f32_e32 v100, 0x3377d1cf, v92
	v_fmac_f32_e32 v100, 0x3f317217, v92
	v_cmp_lt_f32_e64 s[0:1], |v92|, s96
	s_nop 1
	v_cndmask_b32_e64 v92, v92, v100, s[0:1]
	v_cndmask_b32_e32 v100, 0, v167, vcc
	v_sub_f32_e32 v92, v92, v100
	v_sub_f32_e32 v92, v96, v92
	v_min_f32_e32 v96, 0, v88
	v_mul_f32_e64 v88, |v88|, s49
	v_exp_f32_e32 v88, v88
	v_add_f32_e32 v92, -0.5, v92
	v_mul_f32_e32 v92, 0x3fb8aa3b, v92
	v_exp_f32_e32 v92, v92
	v_add_f32_e32 v88, 1.0, v88
	v_cmp_gt_f32_e32 vcc, s90, v88
	v_mul_f32_e32 v92, 0xbfb8aa3b, v92
	s_nop 0
	v_cndmask_b32_e64 v100, 0, 32, vcc
	v_ldexp_f32 v88, v88, v100
	v_log_f32_e32 v88, v88
	v_exp_f32_e32 v92, v92
	v_mul_f32_e32 v100, 0x3f317217, v88
	v_fma_f32 v100, v88, s91, -v100
	v_fmac_f32_e32 v100, 0x3377d1cf, v88
	v_fmac_f32_e32 v100, 0x3f317217, v88
	v_cmp_lt_f32_e64 s[0:1], |v88|, s96
	s_nop 1
	v_cndmask_b32_e64 v88, v88, v100, s[0:1]
	v_cndmask_b32_e32 v100, 0, v167, vcc
	v_sub_f32_e32 v88, v88, v100
	v_sub_f32_e32 v88, v96, v88
	v_min_f32_e32 v96, 0, v93
	v_mul_f32_e64 v93, |v93|, s49
	v_exp_f32_e32 v93, v93
	v_add_f32_e32 v88, -0.5, v88
	v_mul_f32_e32 v88, 0x3fb8aa3b, v88
	v_exp_f32_e32 v88, v88
	v_add_f32_e32 v93, 1.0, v93
	v_cmp_gt_f32_e32 vcc, s90, v93
	v_mul_f32_e32 v88, 0xbfb8aa3b, v88
	s_nop 0
	v_cndmask_b32_e64 v97, 0, 32, vcc
	v_ldexp_f32 v93, v93, v97
	v_log_f32_e32 v93, v93
	v_exp_f32_e32 v88, v88
	v_mul_f32_e32 v97, 0x3f317217, v93
	v_fma_f32 v97, v93, s91, -v97
	v_fmac_f32_e32 v97, 0x3377d1cf, v93
	v_fmac_f32_e32 v97, 0x3f317217, v93
	v_cmp_lt_f32_e64 s[0:1], |v93|, s96
	s_nop 1
	v_cndmask_b32_e64 v93, v93, v97, s[0:1]
	v_cndmask_b32_e32 v97, 0, v167, vcc
	v_sub_f32_e32 v93, v93, v97
	v_sub_f32_e32 v93, v96, v93
	v_min_f32_e32 v96, 0, v89
	v_mul_f32_e64 v89, |v89|, s49
	v_exp_f32_e32 v89, v89
	v_add_f32_e32 v93, -0.5, v93
	v_mul_f32_e32 v93, 0x3fb8aa3b, v93
	v_exp_f32_e32 v93, v93
	v_add_f32_e32 v89, 1.0, v89
	v_cmp_gt_f32_e32 vcc, s90, v89
	v_mul_f32_e32 v93, 0xbfb8aa3b, v93
	s_nop 0
	v_cndmask_b32_e64 v97, 0, 32, vcc
	v_ldexp_f32 v89, v89, v97
	v_log_f32_e32 v89, v89
	v_exp_f32_e32 v93, v93
	v_mul_f32_e32 v97, 0x3f317217, v89
	v_fma_f32 v97, v89, s91, -v97
	v_fmac_f32_e32 v97, 0x3377d1cf, v89
	v_fmac_f32_e32 v97, 0x3f317217, v89
	v_cmp_lt_f32_e64 s[0:1], |v89|, s96
	s_nop 1
	v_cndmask_b32_e64 v89, v89, v97, s[0:1]
	v_cndmask_b32_e32 v97, 0, v167, vcc
	v_sub_f32_e32 v89, v89, v97
	v_sub_f32_e32 v89, v96, v89
	v_min_f32_e32 v96, 0, v94
	v_mul_f32_e64 v94, |v94|, s49
	v_exp_f32_e32 v94, v94
	v_add_f32_e32 v89, -0.5, v89
	v_mul_f32_e32 v89, 0x3fb8aa3b, v89
	v_exp_f32_e32 v89, v89
	v_add_f32_e32 v94, 1.0, v94
	v_cmp_gt_f32_e32 vcc, s90, v94
	v_mul_f32_e32 v89, 0xbfb8aa3b, v89
	s_nop 0
	v_cndmask_b32_e64 v97, 0, 32, vcc
	v_ldexp_f32 v94, v94, v97
	v_log_f32_e32 v94, v94
	v_exp_f32_e32 v89, v89
	v_mul_f32_e32 v97, 0x3f317217, v94
	v_fma_f32 v97, v94, s91, -v97
	v_fmac_f32_e32 v97, 0x3377d1cf, v94
	v_fmac_f32_e32 v97, 0x3f317217, v94
	v_cmp_lt_f32_e64 s[0:1], |v94|, s96
	s_nop 1
	v_cndmask_b32_e64 v94, v94, v97, s[0:1]
	v_cndmask_b32_e32 v97, 0, v167, vcc
	v_sub_f32_e32 v94, v94, v97
	v_sub_f32_e32 v94, v96, v94
	v_min_f32_e32 v96, 0, v90
	v_mul_f32_e64 v90, |v90|, s49
	v_exp_f32_e32 v90, v90
	v_add_f32_e32 v94, -0.5, v94
	v_mul_f32_e32 v94, 0x3fb8aa3b, v94
	v_exp_f32_e32 v94, v94
	v_add_f32_e32 v90, 1.0, v90
	v_cmp_gt_f32_e32 vcc, s90, v90
	v_mul_f32_e32 v94, 0xbfb8aa3b, v94
	s_nop 0
	v_cndmask_b32_e64 v97, 0, 32, vcc
	v_ldexp_f32 v90, v90, v97
	v_log_f32_e32 v90, v90
	v_exp_f32_e32 v94, v94
	v_mul_f32_e32 v97, 0x3f317217, v90
	v_fma_f32 v97, v90, s91, -v97
	v_fmac_f32_e32 v97, 0x3377d1cf, v90
	v_fmac_f32_e32 v97, 0x3f317217, v90
	v_cmp_lt_f32_e64 s[0:1], |v90|, s96
	s_nop 1
	v_cndmask_b32_e64 v90, v90, v97, s[0:1]
	v_cndmask_b32_e32 v97, 0, v167, vcc
	v_sub_f32_e32 v90, v90, v97
	v_sub_f32_e32 v90, v96, v90
	v_min_f32_e32 v96, 0, v95
	v_mul_f32_e64 v95, |v95|, s49
	v_exp_f32_e32 v95, v95
	v_add_f32_e32 v90, -0.5, v90
	v_mul_f32_e32 v90, 0x3fb8aa3b, v90
	v_exp_f32_e32 v90, v90
	v_add_f32_e32 v95, 1.0, v95
	v_cmp_gt_f32_e32 vcc, s90, v95
	v_mul_f32_e32 v90, 0xbfb8aa3b, v90
	s_nop 0
	v_cndmask_b32_e64 v97, 0, 32, vcc
	v_ldexp_f32 v95, v95, v97
	v_log_f32_e32 v95, v95
	v_exp_f32_e32 v90, v90
	v_mul_f32_e32 v97, 0x3f317217, v95
	v_fma_f32 v97, v95, s91, -v97
	v_fmac_f32_e32 v97, 0x3377d1cf, v95
	v_fmac_f32_e32 v97, 0x3f317217, v95
	v_cmp_lt_f32_e64 s[0:1], |v95|, s96
	s_nop 1
	v_cndmask_b32_e64 v95, v95, v97, s[0:1]
	v_cndmask_b32_e32 v97, 0, v167, vcc
	v_sub_f32_e32 v95, v95, v97
	v_sub_f32_e32 v95, v96, v95
	v_min_f32_e32 v96, 0, v91
	v_mul_f32_e64 v91, |v91|, s49
	v_exp_f32_e32 v91, v91
	v_add_f32_e32 v95, -0.5, v95
	v_mul_f32_e32 v95, 0x3fb8aa3b, v95
	v_exp_f32_e32 v95, v95
	v_add_f32_e32 v91, 1.0, v91
	v_cmp_gt_f32_e32 vcc, s90, v91
	v_mul_f32_e32 v95, 0xbfb8aa3b, v95
	s_nop 0
	v_cndmask_b32_e64 v97, 0, 32, vcc
	v_ldexp_f32 v91, v91, v97
	v_log_f32_e32 v91, v91
	v_exp_f32_e32 v95, v95
	v_mul_f32_e32 v97, 0x3f317217, v91
	v_fma_f32 v97, v91, s91, -v97
	v_fmac_f32_e32 v97, 0x3377d1cf, v91
	v_fmac_f32_e32 v97, 0x3f317217, v91
	v_cmp_lt_f32_e64 s[0:1], |v91|, s96
	s_nop 1
	v_cndmask_b32_e64 v91, v91, v97, s[0:1]
	v_cndmask_b32_e32 v97, 0, v167, vcc
	v_sub_f32_e32 v91, v91, v97
	v_sub_f32_e32 v91, v96, v91
	v_add_f32_e32 v91, -0.5, v91
	v_mul_f32_e32 v91, 0x3fb8aa3b, v91
	v_exp_f32_e32 v91, v91
	v_lshlrev_b64 v[96:97], 12, v[104:105]
	v_lshl_add_u64 v[96:97], s[10:11], 0, v[96:97]
	v_lshl_add_u64 v[96:97], v[96:97], 0, v[106:107]
	v_mul_f32_e32 v91, 0xbfb8aa3b, v91
	v_exp_f32_e32 v91, v91
	global_store_dwordx4 v[96:97], v[92:95], off
	global_store_dwordx4 v[96:97], v[88:91], off offset:16
	s_nop 1
	v_mov_b64_e32 v[88:89], v[184:185]
	v_mov_b64_e32 v[90:91], v[186:187]
	s_nop 0
	s_nop 1
	v_mov_b64_e32 v[92:93], v[180:181]
	v_mov_b64_e32 v[94:95], v[182:183]
	v_add_f32_e32 v80, v80, v88
	v_add_f32_e32 v84, v84, v92
	v_min_f32_e32 v88, 0, v84
	v_mul_f32_e64 v84, |v84|, s49
	v_exp_f32_e32 v84, v84
	v_add_f32_e32 v85, v85, v93
	v_add_f32_e32 v81, v81, v89
	v_add_f32_e32 v86, v86, v94
	v_add_f32_e32 v84, 1.0, v84
	v_cmp_gt_f32_e32 vcc, s90, v84
	v_add_f32_e32 v82, v82, v90
	v_add_f32_e32 v87, v87, v95
	v_cndmask_b32_e64 v92, 0, 32, vcc
	v_ldexp_f32 v84, v84, v92
	v_log_f32_e32 v84, v84
	v_add_f32_e32 v83, v83, v91
	v_mul_f32_e32 v92, 0x3f317217, v84
	v_fma_f32 v92, v84, s91, -v92
	v_fmac_f32_e32 v92, 0x3377d1cf, v84
	v_fmac_f32_e32 v92, 0x3f317217, v84
	v_cmp_lt_f32_e64 s[0:1], |v84|, s96
	s_nop 1
	v_cndmask_b32_e64 v84, v84, v92, s[0:1]
	v_cndmask_b32_e32 v92, 0, v167, vcc
	v_sub_f32_e32 v84, v84, v92
	v_sub_f32_e32 v84, v88, v84
	v_min_f32_e32 v88, 0, v80
	v_mul_f32_e64 v80, |v80|, s49
	v_exp_f32_e32 v80, v80
	v_add_f32_e32 v84, -0.5, v84
	v_add_f32_e32 v80, 1.0, v80
	v_cmp_gt_f32_e32 vcc, s90, v80
	s_nop 1
	v_cndmask_b32_e64 v92, 0, 32, vcc
	v_ldexp_f32 v80, v80, v92
	v_log_f32_e32 v80, v80
	s_nop 0
	v_mul_f32_e32 v92, 0x3f317217, v80
	v_fma_f32 v92, v80, s91, -v92
	v_fmac_f32_e32 v92, 0x3377d1cf, v80
	v_fmac_f32_e32 v92, 0x3f317217, v80
	v_cmp_lt_f32_e64 s[0:1], |v80|, s96
	s_nop 1
	v_cndmask_b32_e64 v80, v80, v92, s[0:1]
	v_cndmask_b32_e32 v92, 0, v167, vcc
	v_sub_f32_e32 v80, v80, v92
	v_sub_f32_e32 v80, v88, v80
	v_add_f32_e32 v88, -0.5, v80
	v_mul_f32_e32 v80, 0x3fb8aa3b, v84
	v_mul_f32_e32 v84, 0x3fb8aa3b, v88
	v_min_f32_e32 v88, 0, v85
	v_mul_f32_e64 v85, |v85|, s49
	v_exp_f32_e32 v85, v85
	v_exp_f32_e32 v80, v80
	v_exp_f32_e32 v84, v84
	v_add_f32_e32 v85, 1.0, v85
	v_cmp_gt_f32_e32 vcc, s90, v85
	v_mul_f32_e32 v80, 0xbfb8aa3b, v80
	v_exp_f32_e32 v80, v80
	v_cndmask_b32_e64 v89, 0, 32, vcc
	v_ldexp_f32 v85, v85, v89
	v_log_f32_e32 v85, v85
	v_mul_f32_e32 v84, 0xbfb8aa3b, v84
	v_exp_f32_e32 v84, v84
	v_mul_f32_e32 v89, 0x3f317217, v85
	v_fma_f32 v89, v85, s91, -v89
	v_fmac_f32_e32 v89, 0x3377d1cf, v85
	v_fmac_f32_e32 v89, 0x3f317217, v85
	v_cmp_lt_f32_e64 s[0:1], |v85|, s96
	s_nop 1
	v_cndmask_b32_e64 v85, v85, v89, s[0:1]
	v_cndmask_b32_e32 v89, 0, v167, vcc
	v_sub_f32_e32 v85, v85, v89
	v_sub_f32_e32 v85, v88, v85
	v_min_f32_e32 v88, 0, v81
	v_mul_f32_e64 v81, |v81|, s49
	v_exp_f32_e32 v81, v81
	v_add_f32_e32 v85, -0.5, v85
	v_add_f32_e32 v81, 1.0, v81
	v_cmp_gt_f32_e32 vcc, s90, v81
	s_nop 1
	v_cndmask_b32_e64 v89, 0, 32, vcc
	v_ldexp_f32 v81, v81, v89
	v_log_f32_e32 v81, v81
	s_nop 0
	v_mul_f32_e32 v89, 0x3f317217, v81
	v_fma_f32 v89, v81, s91, -v89
	v_fmac_f32_e32 v89, 0x3377d1cf, v81
	v_fmac_f32_e32 v89, 0x3f317217, v81
	v_cmp_lt_f32_e64 s[0:1], |v81|, s96
	s_nop 1
	v_cndmask_b32_e64 v81, v81, v89, s[0:1]
	v_cndmask_b32_e32 v89, 0, v167, vcc
	v_sub_f32_e32 v81, v81, v89
	v_sub_f32_e32 v81, v88, v81
	v_add_f32_e32 v88, -0.5, v81
	v_mul_f32_e32 v81, 0x3fb8aa3b, v85
	v_mul_f32_e32 v85, 0x3fb8aa3b, v88
	v_min_f32_e32 v88, 0, v86
	v_mul_f32_e64 v86, |v86|, s49
	v_exp_f32_e32 v86, v86
	v_exp_f32_e32 v81, v81
	v_exp_f32_e32 v85, v85
	v_add_f32_e32 v86, 1.0, v86
	v_cmp_gt_f32_e32 vcc, s90, v86
	v_mul_f32_e32 v81, 0xbfb8aa3b, v81
	v_exp_f32_e32 v81, v81
	v_cndmask_b32_e64 v89, 0, 32, vcc
	v_ldexp_f32 v86, v86, v89
	v_log_f32_e32 v86, v86
	v_mul_f32_e32 v85, 0xbfb8aa3b, v85
	v_exp_f32_e32 v85, v85
	v_mul_f32_e32 v89, 0x3f317217, v86
	v_fma_f32 v89, v86, s91, -v89
	v_fmac_f32_e32 v89, 0x3377d1cf, v86
	v_fmac_f32_e32 v89, 0x3f317217, v86
	v_cmp_lt_f32_e64 s[0:1], |v86|, s96
	s_nop 1
	v_cndmask_b32_e64 v86, v86, v89, s[0:1]
	v_cndmask_b32_e32 v89, 0, v167, vcc
	v_sub_f32_e32 v86, v86, v89
	v_sub_f32_e32 v86, v88, v86
	v_min_f32_e32 v88, 0, v82
	v_mul_f32_e64 v82, |v82|, s49
	v_exp_f32_e32 v82, v82
	v_add_f32_e32 v86, -0.5, v86
	v_add_f32_e32 v82, 1.0, v82
	v_cmp_gt_f32_e32 vcc, s90, v82
	s_nop 1
	v_cndmask_b32_e64 v89, 0, 32, vcc
	v_ldexp_f32 v82, v82, v89
	v_log_f32_e32 v82, v82
	s_nop 0
	v_mul_f32_e32 v89, 0x3f317217, v82
	v_fma_f32 v89, v82, s91, -v89
	v_fmac_f32_e32 v89, 0x3377d1cf, v82
	v_fmac_f32_e32 v89, 0x3f317217, v82
	v_cmp_lt_f32_e64 s[0:1], |v82|, s96
	s_nop 1
	v_cndmask_b32_e64 v82, v82, v89, s[0:1]
	v_cndmask_b32_e32 v89, 0, v167, vcc
	v_sub_f32_e32 v82, v82, v89
	v_sub_f32_e32 v82, v88, v82
	v_add_f32_e32 v88, -0.5, v82
	v_mul_f32_e32 v82, 0x3fb8aa3b, v86
	v_mul_f32_e32 v86, 0x3fb8aa3b, v88
	v_min_f32_e32 v88, 0, v87
	v_mul_f32_e64 v87, |v87|, s49
	v_exp_f32_e32 v87, v87
	v_exp_f32_e32 v82, v82
	v_exp_f32_e32 v86, v86
	v_add_f32_e32 v87, 1.0, v87
	v_cmp_gt_f32_e32 vcc, s90, v87
	v_mul_f32_e32 v82, 0xbfb8aa3b, v82
	v_exp_f32_e32 v82, v82
	v_cndmask_b32_e64 v89, 0, 32, vcc
	v_ldexp_f32 v87, v87, v89
	v_log_f32_e32 v87, v87
	v_mul_f32_e32 v86, 0xbfb8aa3b, v86
	v_exp_f32_e32 v86, v86
	v_mul_f32_e32 v89, 0x3f317217, v87
	v_fma_f32 v89, v87, s91, -v89
	v_fmac_f32_e32 v89, 0x3377d1cf, v87
	v_fmac_f32_e32 v89, 0x3f317217, v87
	v_cmp_lt_f32_e64 s[0:1], |v87|, s96
	s_nop 1
	v_cndmask_b32_e64 v87, v87, v89, s[0:1]
	v_cndmask_b32_e32 v89, 0, v167, vcc
	v_sub_f32_e32 v87, v87, v89
	v_sub_f32_e32 v87, v88, v87
	v_min_f32_e32 v88, 0, v83
	v_mul_f32_e64 v83, |v83|, s49
	v_exp_f32_e32 v83, v83
	v_add_f32_e32 v87, -0.5, v87
	v_add_f32_e32 v83, 1.0, v83
	v_cmp_gt_f32_e32 vcc, s90, v83
	s_nop 1
	v_cndmask_b32_e64 v89, 0, 32, vcc
	v_ldexp_f32 v83, v83, v89
	v_log_f32_e32 v83, v83
	s_nop 0
	v_mul_f32_e32 v89, 0x3f317217, v83
	v_fma_f32 v89, v83, s91, -v89
	v_fmac_f32_e32 v89, 0x3377d1cf, v83
	v_fmac_f32_e32 v89, 0x3f317217, v83
	v_cmp_lt_f32_e64 s[0:1], |v83|, s96
	s_nop 1
	v_cndmask_b32_e64 v83, v83, v89, s[0:1]
	v_cndmask_b32_e32 v89, 0, v167, vcc
	v_sub_f32_e32 v83, v83, v89
	v_sub_f32_e32 v83, v88, v83
	v_add_f32_e32 v88, -0.5, v83
	v_mul_f32_e32 v83, 0x3fb8aa3b, v87
	v_exp_f32_e32 v83, v83
	v_mul_f32_e32 v87, 0x3fb8aa3b, v88
	v_exp_f32_e32 v87, v87
	v_mul_f32_e32 v83, 0xbfb8aa3b, v83
	v_exp_f32_e32 v83, v83
	v_mul_f32_e32 v87, 0xbfb8aa3b, v87
	v_exp_f32_e32 v87, v87
	global_store_dwordx4 v[96:97], v[80:83], off offset:512
	global_store_dwordx4 v[96:97], v[84:87], off offset:528
	s_or_b64 exec, exec, s[34:35]
	v_cmp_gt_i32_e32 vcc, s39, v152
	s_and_saveexec_b64 s[34:35], vcc
	s_cbranch_execnz .LBB0_811

.LBB0_805:
	v_readlane_b32 s68, v239, 33
	v_lshlrev_b64 v[74:75], 2, v[154:155]
	v_readlane_b32 s70, v239, 35
	v_readlane_b32 s71, v239, 36
	v_readlane_b32 s69, v239, 34
	v_readlane_b32 s72, v239, 37
	v_lshl_add_u64 v[72:73], s[70:71], 0, v[74:75]
	s_nop 1
	v_mov_b64_e32 v[64:65], v[176:177]
	v_mov_b64_e32 v[66:67], v[178:179]
	s_nop 1
	v_mov_b64_e32 v[68:69], v[172:173]
	v_mov_b64_e32 v[70:71], v[174:175]
	v_readlane_b32 s73, v239, 38
	v_readlane_b32 s74, v239, 39
	v_readlane_b32 s75, v239, 40
	v_readlane_b32 s76, v239, 41
	v_readlane_b32 s77, v239, 42
	v_readlane_b32 s78, v239, 43
	v_readlane_b32 s79, v239, 44
	v_readlane_b32 s80, v239, 45
	v_readlane_b32 s81, v239, 46
	v_readlane_b32 s82, v239, 47
	v_readlane_b32 s83, v239, 48
	v_add_f32_e32 v56, v56, v64
	v_add_f32_e32 v60, v60, v68
	v_min_f32_e32 v64, 0, v60
	v_mul_f32_e64 v60, |v60|, s49
	v_exp_f32_e32 v60, v60
	v_add_f32_e32 v61, v61, v69
	v_add_f32_e32 v57, v57, v65
	v_add_f32_e32 v62, v62, v70
	v_add_f32_e32 v60, 1.0, v60
	v_cmp_gt_f32_e32 vcc, s90, v60
	v_add_f32_e32 v58, v58, v66
	v_add_f32_e32 v63, v63, v71
	v_cndmask_b32_e64 v68, 0, 32, vcc
	v_ldexp_f32 v60, v60, v68
	v_log_f32_e32 v60, v60
	v_add_f32_e32 v59, v59, v67
	v_mul_f32_e32 v68, 0x3f317217, v60
	v_fma_f32 v68, v60, s91, -v68
	v_fmac_f32_e32 v68, 0x3377d1cf, v60
	v_fmac_f32_e32 v68, 0x3f317217, v60
	v_cmp_lt_f32_e64 s[0:1], |v60|, s96
	s_nop 1
	v_cndmask_b32_e64 v60, v60, v68, s[0:1]
	v_cndmask_b32_e32 v68, 0, v167, vcc
	v_sub_f32_e32 v60, v60, v68
	v_sub_f32_e32 v60, v64, v60
	v_min_f32_e32 v64, 0, v56
	v_mul_f32_e64 v56, |v56|, s49
	v_exp_f32_e32 v56, v56
	v_add_f32_e32 v60, -0.5, v60
	v_mul_f32_e32 v60, 0x3fb8aa3b, v60
	v_exp_f32_e32 v60, v60
	v_add_f32_e32 v56, 1.0, v56
	v_cmp_gt_f32_e32 vcc, s90, v56
	v_mul_f32_e32 v60, 0xbfb8aa3b, v60
	s_nop 0
	v_cndmask_b32_e64 v68, 0, 32, vcc
	v_ldexp_f32 v56, v56, v68
	v_log_f32_e32 v56, v56
	v_exp_f32_e32 v60, v60
	v_mul_f32_e32 v68, 0x3f317217, v56
	v_fma_f32 v68, v56, s91, -v68
	v_fmac_f32_e32 v68, 0x3377d1cf, v56
	v_fmac_f32_e32 v68, 0x3f317217, v56
	v_cmp_lt_f32_e64 s[0:1], |v56|, s96
	s_nop 1
	v_cndmask_b32_e64 v56, v56, v68, s[0:1]
	v_cndmask_b32_e32 v68, 0, v167, vcc
	v_sub_f32_e32 v56, v56, v68
	v_sub_f32_e32 v56, v64, v56
	v_min_f32_e32 v64, 0, v61
	v_mul_f32_e64 v61, |v61|, s49
	v_exp_f32_e32 v61, v61
	v_add_f32_e32 v56, -0.5, v56
	v_mul_f32_e32 v56, 0x3fb8aa3b, v56
	v_exp_f32_e32 v56, v56
	v_add_f32_e32 v61, 1.0, v61
	v_cmp_gt_f32_e32 vcc, s90, v61
	v_mul_f32_e32 v56, 0xbfb8aa3b, v56
	s_nop 0
	v_cndmask_b32_e64 v65, 0, 32, vcc
	v_ldexp_f32 v61, v61, v65
	v_log_f32_e32 v61, v61
	v_exp_f32_e32 v56, v56
	v_mul_f32_e32 v65, 0x3f317217, v61
	v_fma_f32 v65, v61, s91, -v65
	v_fmac_f32_e32 v65, 0x3377d1cf, v61
	v_fmac_f32_e32 v65, 0x3f317217, v61
	v_cmp_lt_f32_e64 s[0:1], |v61|, s96
	s_nop 1
	v_cndmask_b32_e64 v61, v61, v65, s[0:1]
	v_cndmask_b32_e32 v65, 0, v167, vcc
	v_sub_f32_e32 v61, v61, v65
	v_sub_f32_e32 v61, v64, v61
	v_min_f32_e32 v64, 0, v57
	v_mul_f32_e64 v57, |v57|, s49
	v_exp_f32_e32 v57, v57
	v_add_f32_e32 v61, -0.5, v61
	v_mul_f32_e32 v61, 0x3fb8aa3b, v61
	v_exp_f32_e32 v61, v61
	v_add_f32_e32 v57, 1.0, v57
	v_cmp_gt_f32_e32 vcc, s90, v57
	v_mul_f32_e32 v61, 0xbfb8aa3b, v61
	s_nop 0
	v_cndmask_b32_e64 v65, 0, 32, vcc
	v_ldexp_f32 v57, v57, v65
	v_log_f32_e32 v57, v57
	v_exp_f32_e32 v61, v61
	v_mul_f32_e32 v65, 0x3f317217, v57
	v_fma_f32 v65, v57, s91, -v65
	v_fmac_f32_e32 v65, 0x3377d1cf, v57
	v_fmac_f32_e32 v65, 0x3f317217, v57
	v_cmp_lt_f32_e64 s[0:1], |v57|, s96
	s_nop 1
	v_cndmask_b32_e64 v57, v57, v65, s[0:1]
	v_cndmask_b32_e32 v65, 0, v167, vcc
	v_sub_f32_e32 v57, v57, v65
	v_sub_f32_e32 v57, v64, v57
	v_min_f32_e32 v64, 0, v62
	v_mul_f32_e64 v62, |v62|, s49
	v_exp_f32_e32 v62, v62
	v_add_f32_e32 v57, -0.5, v57
	v_mul_f32_e32 v57, 0x3fb8aa3b, v57
	v_exp_f32_e32 v57, v57
	v_add_f32_e32 v62, 1.0, v62
	v_cmp_gt_f32_e32 vcc, s90, v62
	v_mul_f32_e32 v57, 0xbfb8aa3b, v57
	s_nop 0
	v_cndmask_b32_e64 v65, 0, 32, vcc
	v_ldexp_f32 v62, v62, v65
	v_log_f32_e32 v62, v62
	v_exp_f32_e32 v57, v57
	v_mul_f32_e32 v65, 0x3f317217, v62
	v_fma_f32 v65, v62, s91, -v65
	v_fmac_f32_e32 v65, 0x3377d1cf, v62
	v_fmac_f32_e32 v65, 0x3f317217, v62
	v_cmp_lt_f32_e64 s[0:1], |v62|, s96
	s_nop 1
	v_cndmask_b32_e64 v62, v62, v65, s[0:1]
	v_cndmask_b32_e32 v65, 0, v167, vcc
	v_sub_f32_e32 v62, v62, v65
	v_sub_f32_e32 v62, v64, v62
	v_min_f32_e32 v64, 0, v58
	v_mul_f32_e64 v58, |v58|, s49
	v_exp_f32_e32 v58, v58
	v_add_f32_e32 v62, -0.5, v62
	v_mul_f32_e32 v62, 0x3fb8aa3b, v62
	v_exp_f32_e32 v62, v62
	v_add_f32_e32 v58, 1.0, v58
	v_cmp_gt_f32_e32 vcc, s90, v58
	v_mul_f32_e32 v62, 0xbfb8aa3b, v62
	s_nop 0
	v_cndmask_b32_e64 v65, 0, 32, vcc
	v_ldexp_f32 v58, v58, v65
	v_log_f32_e32 v58, v58
	v_exp_f32_e32 v62, v62
	v_mul_f32_e32 v65, 0x3f317217, v58
	v_fma_f32 v65, v58, s91, -v65
	v_fmac_f32_e32 v65, 0x3377d1cf, v58
	v_fmac_f32_e32 v65, 0x3f317217, v58
	v_cmp_lt_f32_e64 s[0:1], |v58|, s96
	s_nop 1
	v_cndmask_b32_e64 v58, v58, v65, s[0:1]
	v_cndmask_b32_e32 v65, 0, v167, vcc
	v_sub_f32_e32 v58, v58, v65
	v_sub_f32_e32 v58, v64, v58
	v_min_f32_e32 v64, 0, v63
	v_mul_f32_e64 v63, |v63|, s49
	v_exp_f32_e32 v63, v63
	v_add_f32_e32 v58, -0.5, v58
	v_mul_f32_e32 v58, 0x3fb8aa3b, v58
	v_exp_f32_e32 v58, v58
	v_add_f32_e32 v63, 1.0, v63
	v_cmp_gt_f32_e32 vcc, s90, v63
	v_mul_f32_e32 v58, 0xbfb8aa3b, v58
	s_nop 0
	v_cndmask_b32_e64 v65, 0, 32, vcc
	v_ldexp_f32 v63, v63, v65
	v_log_f32_e32 v63, v63
	v_exp_f32_e32 v58, v58
	v_mul_f32_e32 v65, 0x3f317217, v63
	v_fma_f32 v65, v63, s91, -v65
	v_fmac_f32_e32 v65, 0x3377d1cf, v63
	v_fmac_f32_e32 v65, 0x3f317217, v63
	v_cmp_lt_f32_e64 s[0:1], |v63|, s96
	s_nop 1
	v_cndmask_b32_e64 v63, v63, v65, s[0:1]
	v_cndmask_b32_e32 v65, 0, v167, vcc
	v_sub_f32_e32 v63, v63, v65
	v_sub_f32_e32 v63, v64, v63
	v_min_f32_e32 v64, 0, v59
	v_mul_f32_e64 v59, |v59|, s49
	v_exp_f32_e32 v59, v59
	v_add_f32_e32 v63, -0.5, v63
	v_mul_f32_e32 v63, 0x3fb8aa3b, v63
	v_exp_f32_e32 v63, v63
	v_add_f32_e32 v59, 1.0, v59
	v_cmp_gt_f32_e32 vcc, s90, v59
	v_mul_f32_e32 v63, 0xbfb8aa3b, v63
	s_nop 0
	v_cndmask_b32_e64 v65, 0, 32, vcc
	v_ldexp_f32 v59, v59, v65
	v_log_f32_e32 v59, v59
	v_exp_f32_e32 v63, v63
	v_mul_f32_e32 v65, 0x3f317217, v59
	v_fma_f32 v65, v59, s91, -v65
	v_fmac_f32_e32 v65, 0x3377d1cf, v59
	v_fmac_f32_e32 v65, 0x3f317217, v59
	v_cmp_lt_f32_e64 s[0:1], |v59|, s96
	s_nop 1
	v_cndmask_b32_e64 v59, v59, v65, s[0:1]
	v_cndmask_b32_e32 v65, 0, v167, vcc
	v_sub_f32_e32 v59, v59, v65
	v_sub_f32_e32 v59, v64, v59
	v_add_f32_e32 v59, -0.5, v59
	v_mul_f32_e32 v59, 0x3fb8aa3b, v59
	v_exp_f32_e32 v59, v59
	v_lshlrev_b64 v[64:65], 12, v[152:153]
	v_lshl_add_u64 v[64:65], s[10:11], 0, v[64:65]
	v_lshl_add_u64 v[66:67], v[64:65], 0, v[74:75]
	v_mul_f32_e32 v59, 0xbfb8aa3b, v59
	s_mov_b64 s[0:1], 0x80000
	v_exp_f32_e32 v59, v59
	v_lshl_add_u64 v[64:65], v[66:67], 0, s[0:1]
	s_mov_b32 s0, 0x80000
	v_add_co_u32_e32 v66, vcc, s0, v66
	s_nop 1
	v_addc_co_u32_e32 v67, vcc, 0, v67, vcc
	global_store_dwordx4 v[66:67], v[60:63], off
	global_store_dwordx4 v[64:65], v[56:59], off offset:16
	s_nop 1
	v_mov_b64_e32 v[56:57], v[184:185]
	v_mov_b64_e32 v[58:59], v[186:187]
	s_nop 0
	s_nop 1
	v_mov_b64_e32 v[60:61], v[180:181]
	v_mov_b64_e32 v[62:63], v[182:183]
	v_add_f32_e32 v48, v48, v56
	v_add_f32_e32 v52, v52, v60
	v_min_f32_e32 v56, 0, v52
	v_mul_f32_e64 v52, |v52|, s49
	v_exp_f32_e32 v52, v52
	v_add_f32_e32 v53, v53, v61
	v_add_f32_e32 v49, v49, v57
	v_add_f32_e32 v54, v54, v62
	v_add_f32_e32 v52, 1.0, v52
	v_cmp_gt_f32_e32 vcc, s90, v52
	v_add_f32_e32 v50, v50, v58
	v_add_f32_e32 v55, v55, v63
	v_cndmask_b32_e64 v60, 0, 32, vcc
	v_ldexp_f32 v52, v52, v60
	v_log_f32_e32 v52, v52
	v_add_f32_e32 v51, v51, v59
	v_mul_f32_e32 v60, 0x3f317217, v52
	v_fma_f32 v60, v52, s91, -v60
	v_fmac_f32_e32 v60, 0x3377d1cf, v52
	v_fmac_f32_e32 v60, 0x3f317217, v52
	v_cmp_lt_f32_e64 s[0:1], |v52|, s96
	s_nop 1
	v_cndmask_b32_e64 v52, v52, v60, s[0:1]
	v_cndmask_b32_e32 v60, 0, v167, vcc
	v_sub_f32_e32 v52, v52, v60
	v_sub_f32_e32 v52, v56, v52
	v_min_f32_e32 v56, 0, v48
	v_mul_f32_e64 v48, |v48|, s49
	v_exp_f32_e32 v48, v48
	v_add_f32_e32 v52, -0.5, v52
	v_add_f32_e32 v48, 1.0, v48
	v_cmp_gt_f32_e32 vcc, s90, v48
	s_nop 1
	v_cndmask_b32_e64 v60, 0, 32, vcc
	v_ldexp_f32 v48, v48, v60
	v_log_f32_e32 v48, v48
	s_nop 0
	v_mul_f32_e32 v60, 0x3f317217, v48
	v_fma_f32 v60, v48, s91, -v60
	v_fmac_f32_e32 v60, 0x3377d1cf, v48
	v_fmac_f32_e32 v60, 0x3f317217, v48
	v_cmp_lt_f32_e64 s[0:1], |v48|, s96
	s_nop 1
	v_cndmask_b32_e64 v48, v48, v60, s[0:1]
	v_cndmask_b32_e32 v60, 0, v167, vcc
	v_sub_f32_e32 v48, v48, v60
	v_sub_f32_e32 v48, v56, v48
	v_add_f32_e32 v56, -0.5, v48
	v_mul_f32_e32 v48, 0x3fb8aa3b, v52
	v_mul_f32_e32 v52, 0x3fb8aa3b, v56
	v_min_f32_e32 v56, 0, v53
	v_mul_f32_e64 v53, |v53|, s49
	v_exp_f32_e32 v53, v53
	v_exp_f32_e32 v48, v48
	v_exp_f32_e32 v52, v52
	v_add_f32_e32 v53, 1.0, v53
	v_cmp_gt_f32_e32 vcc, s90, v53
	v_mul_f32_e32 v48, 0xbfb8aa3b, v48
	v_exp_f32_e32 v48, v48
	v_cndmask_b32_e64 v57, 0, 32, vcc
	v_ldexp_f32 v53, v53, v57
	v_log_f32_e32 v53, v53
	v_mul_f32_e32 v52, 0xbfb8aa3b, v52
	v_exp_f32_e32 v52, v52
	v_mul_f32_e32 v57, 0x3f317217, v53
	v_fma_f32 v57, v53, s91, -v57
	v_fmac_f32_e32 v57, 0x3377d1cf, v53
	v_fmac_f32_e32 v57, 0x3f317217, v53
	v_cmp_lt_f32_e64 s[0:1], |v53|, s96
	s_nop 1
	v_cndmask_b32_e64 v53, v53, v57, s[0:1]
	v_cndmask_b32_e32 v57, 0, v167, vcc
	v_sub_f32_e32 v53, v53, v57
	v_sub_f32_e32 v53, v56, v53
	v_min_f32_e32 v56, 0, v49
	v_mul_f32_e64 v49, |v49|, s49
	v_exp_f32_e32 v49, v49
	v_add_f32_e32 v53, -0.5, v53
	v_add_f32_e32 v49, 1.0, v49
	v_cmp_gt_f32_e32 vcc, s90, v49
	s_nop 1
	v_cndmask_b32_e64 v57, 0, 32, vcc
	v_ldexp_f32 v49, v49, v57
	v_log_f32_e32 v49, v49
	s_nop 0
	v_mul_f32_e32 v57, 0x3f317217, v49
	v_fma_f32 v57, v49, s91, -v57
	v_fmac_f32_e32 v57, 0x3377d1cf, v49
	v_fmac_f32_e32 v57, 0x3f317217, v49
	v_cmp_lt_f32_e64 s[0:1], |v49|, s96
	s_nop 1
	v_cndmask_b32_e64 v49, v49, v57, s[0:1]
	v_cndmask_b32_e32 v57, 0, v167, vcc
	v_sub_f32_e32 v49, v49, v57
	v_sub_f32_e32 v49, v56, v49
	v_add_f32_e32 v56, -0.5, v49
	v_mul_f32_e32 v49, 0x3fb8aa3b, v53
	v_mul_f32_e32 v53, 0x3fb8aa3b, v56
	v_min_f32_e32 v56, 0, v54
	v_mul_f32_e64 v54, |v54|, s49
	v_exp_f32_e32 v54, v54
	v_exp_f32_e32 v49, v49
	v_exp_f32_e32 v53, v53
	v_add_f32_e32 v54, 1.0, v54
	v_cmp_gt_f32_e32 vcc, s90, v54
	v_mul_f32_e32 v49, 0xbfb8aa3b, v49
	v_exp_f32_e32 v49, v49
	v_cndmask_b32_e64 v57, 0, 32, vcc
	v_ldexp_f32 v54, v54, v57
	v_log_f32_e32 v54, v54
	v_mul_f32_e32 v53, 0xbfb8aa3b, v53
	v_exp_f32_e32 v53, v53
	v_mul_f32_e32 v57, 0x3f317217, v54
	v_fma_f32 v57, v54, s91, -v57
	v_fmac_f32_e32 v57, 0x3377d1cf, v54
	v_fmac_f32_e32 v57, 0x3f317217, v54
	v_cmp_lt_f32_e64 s[0:1], |v54|, s96
	s_nop 1
	v_cndmask_b32_e64 v54, v54, v57, s[0:1]
	v_cndmask_b32_e32 v57, 0, v167, vcc
	v_sub_f32_e32 v54, v54, v57
	v_sub_f32_e32 v54, v56, v54
	v_min_f32_e32 v56, 0, v50
	v_mul_f32_e64 v50, |v50|, s49
	v_exp_f32_e32 v50, v50
	v_add_f32_e32 v54, -0.5, v54
	v_add_f32_e32 v50, 1.0, v50
	v_cmp_gt_f32_e32 vcc, s90, v50
	s_nop 1
	v_cndmask_b32_e64 v57, 0, 32, vcc
	v_ldexp_f32 v50, v50, v57
	v_log_f32_e32 v50, v50
	s_nop 0
	v_mul_f32_e32 v57, 0x3f317217, v50
	v_fma_f32 v57, v50, s91, -v57
	v_fmac_f32_e32 v57, 0x3377d1cf, v50
	v_fmac_f32_e32 v57, 0x3f317217, v50
	v_cmp_lt_f32_e64 s[0:1], |v50|, s96
	s_nop 1
	v_cndmask_b32_e64 v50, v50, v57, s[0:1]
	v_cndmask_b32_e32 v57, 0, v167, vcc
	v_sub_f32_e32 v50, v50, v57
	v_sub_f32_e32 v50, v56, v50
	v_add_f32_e32 v56, -0.5, v50
	v_mul_f32_e32 v50, 0x3fb8aa3b, v54
	v_mul_f32_e32 v54, 0x3fb8aa3b, v56
	v_min_f32_e32 v56, 0, v55
	v_mul_f32_e64 v55, |v55|, s49
	v_exp_f32_e32 v55, v55
	v_exp_f32_e32 v50, v50
	v_exp_f32_e32 v54, v54
	v_add_f32_e32 v55, 1.0, v55
	v_cmp_gt_f32_e32 vcc, s90, v55
	v_mul_f32_e32 v50, 0xbfb8aa3b, v50
	v_exp_f32_e32 v50, v50
	v_cndmask_b32_e64 v57, 0, 32, vcc
	v_ldexp_f32 v55, v55, v57
	v_log_f32_e32 v55, v55
	v_mul_f32_e32 v54, 0xbfb8aa3b, v54
	v_exp_f32_e32 v54, v54
	v_mul_f32_e32 v57, 0x3f317217, v55
	v_fma_f32 v57, v55, s91, -v57
	v_fmac_f32_e32 v57, 0x3377d1cf, v55
	v_fmac_f32_e32 v57, 0x3f317217, v55
	v_cmp_lt_f32_e64 s[0:1], |v55|, s96
	s_nop 1
	v_cndmask_b32_e64 v55, v55, v57, s[0:1]
	v_cndmask_b32_e32 v57, 0, v167, vcc
	v_sub_f32_e32 v55, v55, v57
	v_sub_f32_e32 v55, v56, v55
	v_min_f32_e32 v56, 0, v51
	v_mul_f32_e64 v51, |v51|, s49
	v_exp_f32_e32 v51, v51
	v_add_f32_e32 v55, -0.5, v55
	v_add_f32_e32 v51, 1.0, v51
	v_cmp_gt_f32_e32 vcc, s90, v51
	s_nop 1
	v_cndmask_b32_e64 v57, 0, 32, vcc
	v_ldexp_f32 v51, v51, v57
	v_log_f32_e32 v51, v51
	s_nop 0
	v_mul_f32_e32 v57, 0x3f317217, v51
	v_fma_f32 v57, v51, s91, -v57
	v_fmac_f32_e32 v57, 0x3377d1cf, v51
	v_fmac_f32_e32 v57, 0x3f317217, v51
	v_cmp_lt_f32_e64 s[0:1], |v51|, s96
	s_nop 1
	v_cndmask_b32_e64 v51, v51, v57, s[0:1]
	v_cndmask_b32_e32 v57, 0, v167, vcc
	v_sub_f32_e32 v51, v51, v57
	v_sub_f32_e32 v51, v56, v51
	v_add_f32_e32 v56, -0.5, v51
	v_mul_f32_e32 v51, 0x3fb8aa3b, v55
	v_exp_f32_e32 v51, v51
	v_mul_f32_e32 v55, 0x3fb8aa3b, v56
	v_exp_f32_e32 v55, v55
	v_mul_f32_e32 v51, 0xbfb8aa3b, v51
	v_exp_f32_e32 v51, v51
	v_mul_f32_e32 v55, 0xbfb8aa3b, v55
	v_exp_f32_e32 v55, v55
	global_store_dwordx4 v[64:65], v[48:51], off offset:512
	global_store_dwordx4 v[64:65], v[52:55], off offset:528
	s_or_b64 exec, exec, s[34:35]
	v_cmp_gt_i32_e32 vcc, s42, v152
	s_and_saveexec_b64 s[34:35], vcc
	s_cbranch_execnz .LBB0_813

.LBB0_807:
	v_readlane_b32 s68, v239, 33
	v_lshlrev_b64 v[42:43], 2, v[154:155]
	v_readlane_b32 s70, v239, 35
	v_readlane_b32 s71, v239, 36
	v_readlane_b32 s69, v239, 34
	v_readlane_b32 s72, v239, 37
	v_lshl_add_u64 v[40:41], s[70:71], 0, v[42:43]
	s_nop 1
	v_mov_b64_e32 v[32:33], v[176:177]
	v_mov_b64_e32 v[34:35], v[178:179]
	s_nop 1
	v_mov_b64_e32 v[36:37], v[172:173]
	v_mov_b64_e32 v[38:39], v[174:175]
	v_readlane_b32 s73, v239, 38
	v_readlane_b32 s74, v239, 39
	v_readlane_b32 s75, v239, 40
	v_readlane_b32 s76, v239, 41
	v_readlane_b32 s77, v239, 42
	v_readlane_b32 s78, v239, 43
	v_readlane_b32 s79, v239, 44
	v_readlane_b32 s80, v239, 45
	v_readlane_b32 s81, v239, 46
	v_readlane_b32 s82, v239, 47
	v_readlane_b32 s83, v239, 48
	v_add_f32_e32 v24, v24, v32
	v_add_f32_e32 v28, v28, v36
	v_min_f32_e32 v32, 0, v28
	v_mul_f32_e64 v28, |v28|, s49
	v_exp_f32_e32 v28, v28
	v_add_f32_e32 v29, v29, v37
	v_add_f32_e32 v25, v25, v33
	v_add_f32_e32 v30, v30, v38
	v_add_f32_e32 v28, 1.0, v28
	v_cmp_gt_f32_e32 vcc, s90, v28
	v_add_f32_e32 v26, v26, v34
	v_add_f32_e32 v31, v31, v39
	v_cndmask_b32_e64 v36, 0, 32, vcc
	v_ldexp_f32 v28, v28, v36
	v_log_f32_e32 v28, v28
	v_add_f32_e32 v27, v27, v35
	v_mul_f32_e32 v36, 0x3f317217, v28
	v_fma_f32 v36, v28, s91, -v36
	v_fmac_f32_e32 v36, 0x3377d1cf, v28
	v_fmac_f32_e32 v36, 0x3f317217, v28
	v_cmp_lt_f32_e64 s[0:1], |v28|, s96
	s_nop 1
	v_cndmask_b32_e64 v28, v28, v36, s[0:1]
	v_cndmask_b32_e32 v36, 0, v167, vcc
	v_sub_f32_e32 v28, v28, v36
	v_sub_f32_e32 v28, v32, v28
	v_min_f32_e32 v32, 0, v24
	v_mul_f32_e64 v24, |v24|, s49
	v_exp_f32_e32 v24, v24
	v_add_f32_e32 v28, -0.5, v28
	v_mul_f32_e32 v28, 0x3fb8aa3b, v28
	v_exp_f32_e32 v28, v28
	v_add_f32_e32 v24, 1.0, v24
	v_cmp_gt_f32_e32 vcc, s90, v24
	v_mul_f32_e32 v28, 0xbfb8aa3b, v28
	s_nop 0
	v_cndmask_b32_e64 v36, 0, 32, vcc
	v_ldexp_f32 v24, v24, v36
	v_log_f32_e32 v24, v24
	v_exp_f32_e32 v28, v28
	v_mul_f32_e32 v36, 0x3f317217, v24
	v_fma_f32 v36, v24, s91, -v36
	v_fmac_f32_e32 v36, 0x3377d1cf, v24
	v_fmac_f32_e32 v36, 0x3f317217, v24
	v_cmp_lt_f32_e64 s[0:1], |v24|, s96
	s_nop 1
	v_cndmask_b32_e64 v24, v24, v36, s[0:1]
	v_cndmask_b32_e32 v36, 0, v167, vcc
	v_sub_f32_e32 v24, v24, v36
	v_sub_f32_e32 v24, v32, v24
	v_min_f32_e32 v32, 0, v29
	v_mul_f32_e64 v29, |v29|, s49
	v_exp_f32_e32 v29, v29
	v_add_f32_e32 v24, -0.5, v24
	v_mul_f32_e32 v24, 0x3fb8aa3b, v24
	v_exp_f32_e32 v24, v24
	v_add_f32_e32 v29, 1.0, v29
	v_cmp_gt_f32_e32 vcc, s90, v29
	v_mul_f32_e32 v24, 0xbfb8aa3b, v24
	s_nop 0
	v_cndmask_b32_e64 v33, 0, 32, vcc
	v_ldexp_f32 v29, v29, v33
	v_log_f32_e32 v29, v29
	v_exp_f32_e32 v24, v24
	v_mul_f32_e32 v33, 0x3f317217, v29
	v_fma_f32 v33, v29, s91, -v33
	v_fmac_f32_e32 v33, 0x3377d1cf, v29
	v_fmac_f32_e32 v33, 0x3f317217, v29
	v_cmp_lt_f32_e64 s[0:1], |v29|, s96
	s_nop 1
	v_cndmask_b32_e64 v29, v29, v33, s[0:1]
	v_cndmask_b32_e32 v33, 0, v167, vcc
	v_sub_f32_e32 v29, v29, v33
	v_sub_f32_e32 v29, v32, v29
	v_min_f32_e32 v32, 0, v25
	v_mul_f32_e64 v25, |v25|, s49
	v_exp_f32_e32 v25, v25
	v_add_f32_e32 v29, -0.5, v29
	v_mul_f32_e32 v29, 0x3fb8aa3b, v29
	v_exp_f32_e32 v29, v29
	v_add_f32_e32 v25, 1.0, v25
	v_cmp_gt_f32_e32 vcc, s90, v25
	v_mul_f32_e32 v29, 0xbfb8aa3b, v29
	s_nop 0
	v_cndmask_b32_e64 v33, 0, 32, vcc
	v_ldexp_f32 v25, v25, v33
	v_log_f32_e32 v25, v25
	v_exp_f32_e32 v29, v29
	v_mul_f32_e32 v33, 0x3f317217, v25
	v_fma_f32 v33, v25, s91, -v33
	v_fmac_f32_e32 v33, 0x3377d1cf, v25
	v_fmac_f32_e32 v33, 0x3f317217, v25
	v_cmp_lt_f32_e64 s[0:1], |v25|, s96
	s_nop 1
	v_cndmask_b32_e64 v25, v25, v33, s[0:1]
	v_cndmask_b32_e32 v33, 0, v167, vcc
	v_sub_f32_e32 v25, v25, v33
	v_sub_f32_e32 v25, v32, v25
	v_min_f32_e32 v32, 0, v30
	v_mul_f32_e64 v30, |v30|, s49
	v_exp_f32_e32 v30, v30
	v_add_f32_e32 v25, -0.5, v25
	v_mul_f32_e32 v25, 0x3fb8aa3b, v25
	v_exp_f32_e32 v25, v25
	v_add_f32_e32 v30, 1.0, v30
	v_cmp_gt_f32_e32 vcc, s90, v30
	v_mul_f32_e32 v25, 0xbfb8aa3b, v25
	s_nop 0
	v_cndmask_b32_e64 v33, 0, 32, vcc
	v_ldexp_f32 v30, v30, v33
	v_log_f32_e32 v30, v30
	v_exp_f32_e32 v25, v25
	v_mul_f32_e32 v33, 0x3f317217, v30
	v_fma_f32 v33, v30, s91, -v33
	v_fmac_f32_e32 v33, 0x3377d1cf, v30
	v_fmac_f32_e32 v33, 0x3f317217, v30
	v_cmp_lt_f32_e64 s[0:1], |v30|, s96
	s_nop 1
	v_cndmask_b32_e64 v30, v30, v33, s[0:1]
	v_cndmask_b32_e32 v33, 0, v167, vcc
	v_sub_f32_e32 v30, v30, v33
	v_sub_f32_e32 v30, v32, v30
	v_min_f32_e32 v32, 0, v26
	v_mul_f32_e64 v26, |v26|, s49
	v_exp_f32_e32 v26, v26
	v_add_f32_e32 v30, -0.5, v30
	v_mul_f32_e32 v30, 0x3fb8aa3b, v30
	v_exp_f32_e32 v30, v30
	v_add_f32_e32 v26, 1.0, v26
	v_cmp_gt_f32_e32 vcc, s90, v26
	v_mul_f32_e32 v30, 0xbfb8aa3b, v30
	s_nop 0
	v_cndmask_b32_e64 v33, 0, 32, vcc
	v_ldexp_f32 v26, v26, v33
	v_log_f32_e32 v26, v26
	v_exp_f32_e32 v30, v30
	v_mul_f32_e32 v33, 0x3f317217, v26
	v_fma_f32 v33, v26, s91, -v33
	v_fmac_f32_e32 v33, 0x3377d1cf, v26
	v_fmac_f32_e32 v33, 0x3f317217, v26
	v_cmp_lt_f32_e64 s[0:1], |v26|, s96
	s_nop 1
	v_cndmask_b32_e64 v26, v26, v33, s[0:1]
	v_cndmask_b32_e32 v33, 0, v167, vcc
	v_sub_f32_e32 v26, v26, v33
	v_sub_f32_e32 v26, v32, v26
	v_min_f32_e32 v32, 0, v31
	v_mul_f32_e64 v31, |v31|, s49
	v_exp_f32_e32 v31, v31
	v_add_f32_e32 v26, -0.5, v26
	v_mul_f32_e32 v26, 0x3fb8aa3b, v26
	v_exp_f32_e32 v26, v26
	v_add_f32_e32 v31, 1.0, v31
	v_cmp_gt_f32_e32 vcc, s90, v31
	v_mul_f32_e32 v26, 0xbfb8aa3b, v26
	s_nop 0
	v_cndmask_b32_e64 v33, 0, 32, vcc
	v_ldexp_f32 v31, v31, v33
	v_log_f32_e32 v31, v31
	v_exp_f32_e32 v26, v26
	v_mul_f32_e32 v33, 0x3f317217, v31
	v_fma_f32 v33, v31, s91, -v33
	v_fmac_f32_e32 v33, 0x3377d1cf, v31
	v_fmac_f32_e32 v33, 0x3f317217, v31
	v_cmp_lt_f32_e64 s[0:1], |v31|, s96
	s_nop 1
	v_cndmask_b32_e64 v31, v31, v33, s[0:1]
	v_cndmask_b32_e32 v33, 0, v167, vcc
	v_sub_f32_e32 v31, v31, v33
	v_sub_f32_e32 v31, v32, v31
	v_min_f32_e32 v32, 0, v27
	v_mul_f32_e64 v27, |v27|, s49
	v_exp_f32_e32 v27, v27
	v_add_f32_e32 v31, -0.5, v31
	v_mul_f32_e32 v31, 0x3fb8aa3b, v31
	v_exp_f32_e32 v31, v31
	v_add_f32_e32 v27, 1.0, v27
	v_cmp_gt_f32_e32 vcc, s90, v27
	v_mul_f32_e32 v31, 0xbfb8aa3b, v31
	s_nop 0
	v_cndmask_b32_e64 v33, 0, 32, vcc
	v_ldexp_f32 v27, v27, v33
	v_log_f32_e32 v27, v27
	v_exp_f32_e32 v31, v31
	v_mul_f32_e32 v33, 0x3f317217, v27
	v_fma_f32 v33, v27, s91, -v33
	v_fmac_f32_e32 v33, 0x3377d1cf, v27
	v_fmac_f32_e32 v33, 0x3f317217, v27
	v_cmp_lt_f32_e64 s[0:1], |v27|, s96
	s_nop 1
	v_cndmask_b32_e64 v27, v27, v33, s[0:1]
	v_cndmask_b32_e32 v33, 0, v167, vcc
	v_sub_f32_e32 v27, v27, v33
	v_sub_f32_e32 v27, v32, v27
	v_add_f32_e32 v27, -0.5, v27
	v_mul_f32_e32 v27, 0x3fb8aa3b, v27
	v_exp_f32_e32 v27, v27
	v_lshlrev_b64 v[32:33], 12, v[152:153]
	v_lshl_add_u64 v[32:33], s[10:11], 0, v[32:33]
	v_lshl_add_u64 v[34:35], v[32:33], 0, v[42:43]
	v_mul_f32_e32 v27, 0xbfb8aa3b, v27
	s_mov_b64 s[0:1], 0xa0000
	v_exp_f32_e32 v27, v27
	v_lshl_add_u64 v[32:33], v[34:35], 0, s[0:1]
	s_mov_b32 s0, 0xa0000
	v_add_co_u32_e32 v34, vcc, s0, v34
	s_nop 1
	v_addc_co_u32_e32 v35, vcc, 0, v35, vcc
	global_store_dwordx4 v[34:35], v[28:31], off
	global_store_dwordx4 v[32:33], v[24:27], off offset:16
	s_nop 1
	v_mov_b64_e32 v[24:25], v[184:185]
	v_mov_b64_e32 v[26:27], v[186:187]
	s_nop 0
	s_nop 1
	v_mov_b64_e32 v[28:29], v[180:181]
	v_mov_b64_e32 v[30:31], v[182:183]
	v_add_f32_e32 v16, v16, v24
	v_add_f32_e32 v20, v20, v28
	v_min_f32_e32 v24, 0, v20
	v_mul_f32_e64 v20, |v20|, s49
	v_exp_f32_e32 v20, v20
	v_add_f32_e32 v21, v21, v29
	v_add_f32_e32 v17, v17, v25
	v_add_f32_e32 v22, v22, v30
	v_add_f32_e32 v20, 1.0, v20
	v_cmp_gt_f32_e32 vcc, s90, v20
	v_add_f32_e32 v18, v18, v26
	v_add_f32_e32 v23, v23, v31
	v_cndmask_b32_e64 v28, 0, 32, vcc
	v_ldexp_f32 v20, v20, v28
	v_log_f32_e32 v20, v20
	v_add_f32_e32 v19, v19, v27
	v_mul_f32_e32 v28, 0x3f317217, v20
	v_fma_f32 v28, v20, s91, -v28
	v_fmac_f32_e32 v28, 0x3377d1cf, v20
	v_fmac_f32_e32 v28, 0x3f317217, v20
	v_cmp_lt_f32_e64 s[0:1], |v20|, s96
	s_nop 1
	v_cndmask_b32_e64 v20, v20, v28, s[0:1]
	v_cndmask_b32_e32 v28, 0, v167, vcc
	v_sub_f32_e32 v20, v20, v28
	v_sub_f32_e32 v20, v24, v20
	v_min_f32_e32 v24, 0, v16
	v_mul_f32_e64 v16, |v16|, s49
	v_exp_f32_e32 v16, v16
	v_add_f32_e32 v20, -0.5, v20
	v_add_f32_e32 v16, 1.0, v16
	v_cmp_gt_f32_e32 vcc, s90, v16
	s_nop 1
	v_cndmask_b32_e64 v28, 0, 32, vcc
	v_ldexp_f32 v16, v16, v28
	v_log_f32_e32 v16, v16
	s_nop 0
	v_mul_f32_e32 v28, 0x3f317217, v16
	v_fma_f32 v28, v16, s91, -v28
	v_fmac_f32_e32 v28, 0x3377d1cf, v16
	v_fmac_f32_e32 v28, 0x3f317217, v16
	v_cmp_lt_f32_e64 s[0:1], |v16|, s96
	s_nop 1
	v_cndmask_b32_e64 v16, v16, v28, s[0:1]
	v_cndmask_b32_e32 v28, 0, v167, vcc
	v_sub_f32_e32 v16, v16, v28
	v_sub_f32_e32 v16, v24, v16
	v_add_f32_e32 v24, -0.5, v16
	v_mul_f32_e32 v16, 0x3fb8aa3b, v20
	v_mul_f32_e32 v20, 0x3fb8aa3b, v24
	v_min_f32_e32 v24, 0, v21
	v_mul_f32_e64 v21, |v21|, s49
	v_exp_f32_e32 v21, v21
	v_exp_f32_e32 v16, v16
	v_exp_f32_e32 v20, v20
	v_add_f32_e32 v21, 1.0, v21
	v_cmp_gt_f32_e32 vcc, s90, v21
	v_mul_f32_e32 v16, 0xbfb8aa3b, v16
	v_exp_f32_e32 v16, v16
	v_cndmask_b32_e64 v25, 0, 32, vcc
	v_ldexp_f32 v21, v21, v25
	v_log_f32_e32 v21, v21
	v_mul_f32_e32 v20, 0xbfb8aa3b, v20
	v_exp_f32_e32 v20, v20
	v_mul_f32_e32 v25, 0x3f317217, v21
	v_fma_f32 v25, v21, s91, -v25
	v_fmac_f32_e32 v25, 0x3377d1cf, v21
	v_fmac_f32_e32 v25, 0x3f317217, v21
	v_cmp_lt_f32_e64 s[0:1], |v21|, s96
	s_nop 1
	v_cndmask_b32_e64 v21, v21, v25, s[0:1]
	v_cndmask_b32_e32 v25, 0, v167, vcc
	v_sub_f32_e32 v21, v21, v25
	v_sub_f32_e32 v21, v24, v21
	v_min_f32_e32 v24, 0, v17
	v_mul_f32_e64 v17, |v17|, s49
	v_exp_f32_e32 v17, v17
	v_add_f32_e32 v21, -0.5, v21
	v_add_f32_e32 v17, 1.0, v17
	v_cmp_gt_f32_e32 vcc, s90, v17
	s_nop 1
	v_cndmask_b32_e64 v25, 0, 32, vcc
	v_ldexp_f32 v17, v17, v25
	v_log_f32_e32 v17, v17
	s_nop 0
	v_mul_f32_e32 v25, 0x3f317217, v17
	v_fma_f32 v25, v17, s91, -v25
	v_fmac_f32_e32 v25, 0x3377d1cf, v17
	v_fmac_f32_e32 v25, 0x3f317217, v17
	v_cmp_lt_f32_e64 s[0:1], |v17|, s96
	s_nop 1
	v_cndmask_b32_e64 v17, v17, v25, s[0:1]
	v_cndmask_b32_e32 v25, 0, v167, vcc
	v_sub_f32_e32 v17, v17, v25
	v_sub_f32_e32 v17, v24, v17
	v_add_f32_e32 v24, -0.5, v17
	v_mul_f32_e32 v17, 0x3fb8aa3b, v21
	v_mul_f32_e32 v21, 0x3fb8aa3b, v24
	v_min_f32_e32 v24, 0, v22
	v_mul_f32_e64 v22, |v22|, s49
	v_exp_f32_e32 v22, v22
	v_exp_f32_e32 v17, v17
	v_exp_f32_e32 v21, v21
	v_add_f32_e32 v22, 1.0, v22
	v_cmp_gt_f32_e32 vcc, s90, v22
	v_mul_f32_e32 v17, 0xbfb8aa3b, v17
	v_exp_f32_e32 v17, v17
	v_cndmask_b32_e64 v25, 0, 32, vcc
	v_ldexp_f32 v22, v22, v25
	v_log_f32_e32 v22, v22
	v_mul_f32_e32 v21, 0xbfb8aa3b, v21
	v_exp_f32_e32 v21, v21
	v_mul_f32_e32 v25, 0x3f317217, v22
	v_fma_f32 v25, v22, s91, -v25
	v_fmac_f32_e32 v25, 0x3377d1cf, v22
	v_fmac_f32_e32 v25, 0x3f317217, v22
	v_cmp_lt_f32_e64 s[0:1], |v22|, s96
	s_nop 1
	v_cndmask_b32_e64 v22, v22, v25, s[0:1]
	v_cndmask_b32_e32 v25, 0, v167, vcc
	v_sub_f32_e32 v22, v22, v25
	v_sub_f32_e32 v22, v24, v22
	v_min_f32_e32 v24, 0, v18
	v_mul_f32_e64 v18, |v18|, s49
	v_exp_f32_e32 v18, v18
	v_add_f32_e32 v22, -0.5, v22
	v_add_f32_e32 v18, 1.0, v18
	v_cmp_gt_f32_e32 vcc, s90, v18
	s_nop 1
	v_cndmask_b32_e64 v25, 0, 32, vcc
	v_ldexp_f32 v18, v18, v25
	v_log_f32_e32 v18, v18
	s_nop 0
	v_mul_f32_e32 v25, 0x3f317217, v18
	v_fma_f32 v25, v18, s91, -v25
	v_fmac_f32_e32 v25, 0x3377d1cf, v18
	v_fmac_f32_e32 v25, 0x3f317217, v18
	v_cmp_lt_f32_e64 s[0:1], |v18|, s96
	s_nop 1
	v_cndmask_b32_e64 v18, v18, v25, s[0:1]
	v_cndmask_b32_e32 v25, 0, v167, vcc
	v_sub_f32_e32 v18, v18, v25
	v_sub_f32_e32 v18, v24, v18
	v_add_f32_e32 v24, -0.5, v18
	v_mul_f32_e32 v18, 0x3fb8aa3b, v22
	v_mul_f32_e32 v22, 0x3fb8aa3b, v24
	v_min_f32_e32 v24, 0, v23
	v_mul_f32_e64 v23, |v23|, s49
	v_exp_f32_e32 v23, v23
	v_exp_f32_e32 v18, v18
	v_exp_f32_e32 v22, v22
	v_add_f32_e32 v23, 1.0, v23
	v_cmp_gt_f32_e32 vcc, s90, v23
	v_mul_f32_e32 v18, 0xbfb8aa3b, v18
	v_exp_f32_e32 v18, v18
	v_cndmask_b32_e64 v25, 0, 32, vcc
	v_ldexp_f32 v23, v23, v25
	v_log_f32_e32 v23, v23
	v_mul_f32_e32 v22, 0xbfb8aa3b, v22
	v_exp_f32_e32 v22, v22
	v_mul_f32_e32 v25, 0x3f317217, v23
	v_fma_f32 v25, v23, s91, -v25
	v_fmac_f32_e32 v25, 0x3377d1cf, v23
	v_fmac_f32_e32 v25, 0x3f317217, v23
	v_cmp_lt_f32_e64 s[0:1], |v23|, s96
	s_nop 1
	v_cndmask_b32_e64 v23, v23, v25, s[0:1]
	v_cndmask_b32_e32 v25, 0, v167, vcc
	v_sub_f32_e32 v23, v23, v25
	v_sub_f32_e32 v23, v24, v23
	v_min_f32_e32 v24, 0, v19
	v_mul_f32_e64 v19, |v19|, s49
	v_exp_f32_e32 v19, v19
	v_add_f32_e32 v23, -0.5, v23
	v_add_f32_e32 v19, 1.0, v19
	v_cmp_gt_f32_e32 vcc, s90, v19
	s_nop 1
	v_cndmask_b32_e64 v25, 0, 32, vcc
	v_ldexp_f32 v19, v19, v25
	v_log_f32_e32 v19, v19
	s_nop 0
	v_mul_f32_e32 v25, 0x3f317217, v19
	v_fma_f32 v25, v19, s91, -v25
	v_fmac_f32_e32 v25, 0x3377d1cf, v19
	v_fmac_f32_e32 v25, 0x3f317217, v19
	v_cmp_lt_f32_e64 s[0:1], |v19|, s96
	s_nop 1
	v_cndmask_b32_e64 v19, v19, v25, s[0:1]
	v_cndmask_b32_e32 v25, 0, v167, vcc
	v_sub_f32_e32 v19, v19, v25
	v_sub_f32_e32 v19, v24, v19
	v_add_f32_e32 v24, -0.5, v19
	v_mul_f32_e32 v19, 0x3fb8aa3b, v23
	v_exp_f32_e32 v19, v19
	v_mul_f32_e32 v23, 0x3fb8aa3b, v24
	v_exp_f32_e32 v23, v23
	v_mul_f32_e32 v19, 0xbfb8aa3b, v19
	v_exp_f32_e32 v19, v19
	v_mul_f32_e32 v23, 0xbfb8aa3b, v23
	v_exp_f32_e32 v23, v23
	global_store_dwordx4 v[32:33], v[16:19], off offset:512
	global_store_dwordx4 v[32:33], v[20:23], off offset:528
	s_or_b64 exec, exec, s[34:35]
	v_cmp_gt_i32_e32 vcc, s48, v152
	s_and_saveexec_b64 s[34:35], vcc
	s_cbranch_execnz .LBB0_815
	s_branch .LBB0_816

.LBB0_809:
	v_readlane_b32 s68, v239, 33
	v_lshlrev_b64 v[122:123], 2, v[154:155]
	v_readlane_b32 s70, v239, 35
	v_readlane_b32 s71, v239, 36
	v_or_b32_e32 v120, 16, v152
	v_ashrrev_i32_e32 v121, 31, v120
	v_lshl_add_u64 v[124:125], s[70:71], 0, v[122:123]
	s_nop 1
	v_mov_b64_e32 v[112:113], v[176:177]
	v_mov_b64_e32 v[114:115], v[178:179]
	s_nop 1
	v_mov_b64_e32 v[116:117], v[172:173]
	v_mov_b64_e32 v[118:119], v[174:175]
	v_readlane_b32 s69, v239, 34
	v_readlane_b32 s72, v239, 37
	v_readlane_b32 s73, v239, 38
	v_readlane_b32 s74, v239, 39
	v_readlane_b32 s75, v239, 40
	v_readlane_b32 s76, v239, 41
	v_readlane_b32 s77, v239, 42
	v_readlane_b32 s78, v239, 43
	v_readlane_b32 s79, v239, 44
	v_readlane_b32 s80, v239, 45
	v_readlane_b32 s81, v239, 46
	v_readlane_b32 s82, v239, 47
	v_readlane_b32 s83, v239, 48
	v_add_f32_e32 v104, v104, v112
	v_add_f32_e32 v108, v108, v116
	v_min_f32_e32 v112, 0, v108
	v_mul_f32_e64 v108, |v108|, s49
	v_exp_f32_e32 v108, v108
	v_add_f32_e32 v109, v109, v117
	v_add_f32_e32 v105, v105, v113
	v_add_f32_e32 v110, v110, v118
	v_add_f32_e32 v108, 1.0, v108
	v_cmp_gt_f32_e32 vcc, s90, v108
	v_add_f32_e32 v106, v106, v114
	v_add_f32_e32 v111, v111, v119
	v_cndmask_b32_e64 v116, 0, 32, vcc
	v_ldexp_f32 v108, v108, v116
	v_log_f32_e32 v108, v108
	v_add_f32_e32 v107, v107, v115
	v_mul_f32_e32 v116, 0x3f317217, v108
	v_fma_f32 v116, v108, s91, -v116
	v_fmac_f32_e32 v116, 0x3377d1cf, v108
	v_fmac_f32_e32 v116, 0x3f317217, v108
	v_cmp_lt_f32_e64 s[0:1], |v108|, s96
	s_nop 1
	v_cndmask_b32_e64 v108, v108, v116, s[0:1]
	v_cndmask_b32_e32 v116, 0, v167, vcc
	v_sub_f32_e32 v108, v108, v116
	v_sub_f32_e32 v108, v112, v108
	v_min_f32_e32 v112, 0, v104
	v_mul_f32_e64 v104, |v104|, s49
	v_exp_f32_e32 v104, v104
	v_add_f32_e32 v108, -0.5, v108
	v_mul_f32_e32 v108, 0x3fb8aa3b, v108
	v_exp_f32_e32 v108, v108
	v_add_f32_e32 v104, 1.0, v104
	v_cmp_gt_f32_e32 vcc, s90, v104
	v_mul_f32_e32 v108, 0xbfb8aa3b, v108
	s_nop 0
	v_cndmask_b32_e64 v116, 0, 32, vcc
	v_ldexp_f32 v104, v104, v116
	v_log_f32_e32 v104, v104
	v_exp_f32_e32 v108, v108
	v_mul_f32_e32 v116, 0x3f317217, v104
	v_fma_f32 v116, v104, s91, -v116
	v_fmac_f32_e32 v116, 0x3377d1cf, v104
	v_fmac_f32_e32 v116, 0x3f317217, v104
	v_cmp_lt_f32_e64 s[0:1], |v104|, s96
	s_nop 1
	v_cndmask_b32_e64 v104, v104, v116, s[0:1]
	v_cndmask_b32_e32 v116, 0, v167, vcc
	v_sub_f32_e32 v104, v104, v116
	v_sub_f32_e32 v104, v112, v104
	v_min_f32_e32 v112, 0, v109
	v_mul_f32_e64 v109, |v109|, s49
	v_exp_f32_e32 v109, v109
	v_add_f32_e32 v104, -0.5, v104
	v_mul_f32_e32 v104, 0x3fb8aa3b, v104
	v_exp_f32_e32 v104, v104
	v_add_f32_e32 v109, 1.0, v109
	v_cmp_gt_f32_e32 vcc, s90, v109
	v_mul_f32_e32 v104, 0xbfb8aa3b, v104
	s_nop 0
	v_cndmask_b32_e64 v113, 0, 32, vcc
	v_ldexp_f32 v109, v109, v113
	v_log_f32_e32 v109, v109
	v_exp_f32_e32 v104, v104
	v_mul_f32_e32 v113, 0x3f317217, v109
	v_fma_f32 v113, v109, s91, -v113
	v_fmac_f32_e32 v113, 0x3377d1cf, v109
	v_fmac_f32_e32 v113, 0x3f317217, v109
	v_cmp_lt_f32_e64 s[0:1], |v109|, s96
	s_nop 1
	v_cndmask_b32_e64 v109, v109, v113, s[0:1]
	v_cndmask_b32_e32 v113, 0, v167, vcc
	v_sub_f32_e32 v109, v109, v113
	v_sub_f32_e32 v109, v112, v109
	v_min_f32_e32 v112, 0, v105
	v_mul_f32_e64 v105, |v105|, s49
	v_exp_f32_e32 v105, v105
	v_add_f32_e32 v109, -0.5, v109
	v_mul_f32_e32 v109, 0x3fb8aa3b, v109
	v_exp_f32_e32 v109, v109
	v_add_f32_e32 v105, 1.0, v105
	v_cmp_gt_f32_e32 vcc, s90, v105
	v_mul_f32_e32 v109, 0xbfb8aa3b, v109
	s_nop 0
	v_cndmask_b32_e64 v113, 0, 32, vcc
	v_ldexp_f32 v105, v105, v113
	v_log_f32_e32 v105, v105
	v_exp_f32_e32 v109, v109
	v_mul_f32_e32 v113, 0x3f317217, v105
	v_fma_f32 v113, v105, s91, -v113
	v_fmac_f32_e32 v113, 0x3377d1cf, v105
	v_fmac_f32_e32 v113, 0x3f317217, v105
	v_cmp_lt_f32_e64 s[0:1], |v105|, s96
	s_nop 1
	v_cndmask_b32_e64 v105, v105, v113, s[0:1]
	v_cndmask_b32_e32 v113, 0, v167, vcc
	v_sub_f32_e32 v105, v105, v113
	v_sub_f32_e32 v105, v112, v105
	v_min_f32_e32 v112, 0, v110
	v_mul_f32_e64 v110, |v110|, s49
	v_exp_f32_e32 v110, v110
	v_add_f32_e32 v105, -0.5, v105
	v_mul_f32_e32 v105, 0x3fb8aa3b, v105
	v_exp_f32_e32 v105, v105
	v_add_f32_e32 v110, 1.0, v110
	v_cmp_gt_f32_e32 vcc, s90, v110
	v_mul_f32_e32 v105, 0xbfb8aa3b, v105
	s_nop 0
	v_cndmask_b32_e64 v113, 0, 32, vcc
	v_ldexp_f32 v110, v110, v113
	v_log_f32_e32 v110, v110
	v_exp_f32_e32 v105, v105
	v_mul_f32_e32 v113, 0x3f317217, v110
	v_fma_f32 v113, v110, s91, -v113
	v_fmac_f32_e32 v113, 0x3377d1cf, v110
	v_fmac_f32_e32 v113, 0x3f317217, v110
	v_cmp_lt_f32_e64 s[0:1], |v110|, s96
	s_nop 1
	v_cndmask_b32_e64 v110, v110, v113, s[0:1]
	v_cndmask_b32_e32 v113, 0, v167, vcc
	v_sub_f32_e32 v110, v110, v113
	v_sub_f32_e32 v110, v112, v110
	v_min_f32_e32 v112, 0, v106
	v_mul_f32_e64 v106, |v106|, s49
	v_exp_f32_e32 v106, v106
	v_add_f32_e32 v110, -0.5, v110
	v_mul_f32_e32 v110, 0x3fb8aa3b, v110
	v_exp_f32_e32 v110, v110
	v_add_f32_e32 v106, 1.0, v106
	v_cmp_gt_f32_e32 vcc, s90, v106
	v_mul_f32_e32 v110, 0xbfb8aa3b, v110
	s_nop 0
	v_cndmask_b32_e64 v113, 0, 32, vcc
	v_ldexp_f32 v106, v106, v113
	v_log_f32_e32 v106, v106
	v_exp_f32_e32 v110, v110
	v_mul_f32_e32 v113, 0x3f317217, v106
	v_fma_f32 v113, v106, s91, -v113
	v_fmac_f32_e32 v113, 0x3377d1cf, v106
	v_fmac_f32_e32 v113, 0x3f317217, v106
	v_cmp_lt_f32_e64 s[0:1], |v106|, s96
	s_nop 1
	v_cndmask_b32_e64 v106, v106, v113, s[0:1]
	v_cndmask_b32_e32 v113, 0, v167, vcc
	v_sub_f32_e32 v106, v106, v113
	v_sub_f32_e32 v106, v112, v106
	v_min_f32_e32 v112, 0, v111
	v_mul_f32_e64 v111, |v111|, s49
	v_exp_f32_e32 v111, v111
	v_add_f32_e32 v106, -0.5, v106
	v_mul_f32_e32 v106, 0x3fb8aa3b, v106
	v_exp_f32_e32 v106, v106
	v_add_f32_e32 v111, 1.0, v111
	v_cmp_gt_f32_e32 vcc, s90, v111
	v_mul_f32_e32 v106, 0xbfb8aa3b, v106
	s_nop 0
	v_cndmask_b32_e64 v113, 0, 32, vcc
	v_ldexp_f32 v111, v111, v113
	v_log_f32_e32 v111, v111
	v_exp_f32_e32 v106, v106
	v_mul_f32_e32 v113, 0x3f317217, v111
	v_fma_f32 v113, v111, s91, -v113
	v_fmac_f32_e32 v113, 0x3377d1cf, v111
	v_fmac_f32_e32 v113, 0x3f317217, v111
	v_cmp_lt_f32_e64 s[0:1], |v111|, s96
	s_nop 1
	v_cndmask_b32_e64 v111, v111, v113, s[0:1]
	v_cndmask_b32_e32 v113, 0, v167, vcc
	v_sub_f32_e32 v111, v111, v113
	v_sub_f32_e32 v111, v112, v111
	v_min_f32_e32 v112, 0, v107
	v_mul_f32_e64 v107, |v107|, s49
	v_exp_f32_e32 v107, v107
	v_add_f32_e32 v111, -0.5, v111
	v_mul_f32_e32 v111, 0x3fb8aa3b, v111
	v_exp_f32_e32 v111, v111
	v_add_f32_e32 v107, 1.0, v107
	v_cmp_gt_f32_e32 vcc, s90, v107
	v_mul_f32_e32 v111, 0xbfb8aa3b, v111
	s_nop 0
	v_cndmask_b32_e64 v113, 0, 32, vcc
	v_ldexp_f32 v107, v107, v113
	v_log_f32_e32 v107, v107
	v_exp_f32_e32 v111, v111
	v_mul_f32_e32 v113, 0x3f317217, v107
	v_fma_f32 v113, v107, s91, -v113
	v_fmac_f32_e32 v113, 0x3377d1cf, v107
	v_fmac_f32_e32 v113, 0x3f317217, v107
	v_cmp_lt_f32_e64 s[0:1], |v107|, s96
	s_nop 1
	v_cndmask_b32_e64 v107, v107, v113, s[0:1]
	v_cndmask_b32_e32 v113, 0, v167, vcc
	v_sub_f32_e32 v107, v107, v113
	v_sub_f32_e32 v107, v112, v107
	v_add_f32_e32 v107, -0.5, v107
	v_mul_f32_e32 v107, 0x3fb8aa3b, v107
	v_exp_f32_e32 v107, v107
	v_lshlrev_b64 v[112:113], 12, v[120:121]
	v_lshl_add_u64 v[112:113], s[10:11], 0, v[112:113]
	v_lshl_add_u64 v[112:113], v[112:113], 0, v[122:123]
	v_mul_f32_e32 v107, 0xbfb8aa3b, v107
	v_exp_f32_e32 v107, v107
	global_store_dwordx4 v[112:113], v[108:111], off
	global_store_dwordx4 v[112:113], v[104:107], off offset:16
	s_nop 1
	v_mov_b64_e32 v[104:105], v[184:185]
	v_mov_b64_e32 v[106:107], v[186:187]
	s_nop 0
	s_nop 1
	v_mov_b64_e32 v[108:109], v[180:181]
	v_mov_b64_e32 v[110:111], v[182:183]
	v_add_f32_e32 v96, v96, v104
	v_add_f32_e32 v100, v100, v108
	v_min_f32_e32 v104, 0, v100
	v_mul_f32_e64 v100, |v100|, s49
	v_exp_f32_e32 v100, v100
	v_add_f32_e32 v101, v101, v109
	v_add_f32_e32 v97, v97, v105
	v_add_f32_e32 v102, v102, v110
	v_add_f32_e32 v100, 1.0, v100
	v_cmp_gt_f32_e32 vcc, s90, v100
	v_add_f32_e32 v98, v98, v106
	v_add_f32_e32 v103, v103, v111
	v_cndmask_b32_e64 v108, 0, 32, vcc
	v_ldexp_f32 v100, v100, v108
	v_log_f32_e32 v100, v100
	v_add_f32_e32 v99, v99, v107
	v_mul_f32_e32 v108, 0x3f317217, v100
	v_fma_f32 v108, v100, s91, -v108
	v_fmac_f32_e32 v108, 0x3377d1cf, v100
	v_fmac_f32_e32 v108, 0x3f317217, v100
	v_cmp_lt_f32_e64 s[0:1], |v100|, s96
	s_nop 1
	v_cndmask_b32_e64 v100, v100, v108, s[0:1]
	v_cndmask_b32_e32 v108, 0, v167, vcc
	v_sub_f32_e32 v100, v100, v108
	v_sub_f32_e32 v100, v104, v100
	v_min_f32_e32 v104, 0, v96
	v_mul_f32_e64 v96, |v96|, s49
	v_exp_f32_e32 v96, v96
	v_add_f32_e32 v100, -0.5, v100
	v_add_f32_e32 v96, 1.0, v96
	v_cmp_gt_f32_e32 vcc, s90, v96
	s_nop 1
	v_cndmask_b32_e64 v108, 0, 32, vcc
	v_ldexp_f32 v96, v96, v108
	v_log_f32_e32 v96, v96
	s_nop 0
	v_mul_f32_e32 v108, 0x3f317217, v96
	v_fma_f32 v108, v96, s91, -v108
	v_fmac_f32_e32 v108, 0x3377d1cf, v96
	v_fmac_f32_e32 v108, 0x3f317217, v96
	v_cmp_lt_f32_e64 s[0:1], |v96|, s96
	s_nop 1
	v_cndmask_b32_e64 v96, v96, v108, s[0:1]
	v_cndmask_b32_e32 v108, 0, v167, vcc
	v_sub_f32_e32 v96, v96, v108
	v_sub_f32_e32 v96, v104, v96
	v_add_f32_e32 v104, -0.5, v96
	v_mul_f32_e32 v96, 0x3fb8aa3b, v100
	v_mul_f32_e32 v100, 0x3fb8aa3b, v104
	v_min_f32_e32 v104, 0, v101
	v_mul_f32_e64 v101, |v101|, s49
	v_exp_f32_e32 v101, v101
	v_exp_f32_e32 v96, v96
	v_exp_f32_e32 v100, v100
	v_add_f32_e32 v101, 1.0, v101
	v_cmp_gt_f32_e32 vcc, s90, v101
	v_mul_f32_e32 v96, 0xbfb8aa3b, v96
	v_exp_f32_e32 v96, v96
	v_cndmask_b32_e64 v105, 0, 32, vcc
	v_ldexp_f32 v101, v101, v105
	v_log_f32_e32 v101, v101
	v_mul_f32_e32 v100, 0xbfb8aa3b, v100
	v_exp_f32_e32 v100, v100
	v_mul_f32_e32 v105, 0x3f317217, v101
	v_fma_f32 v105, v101, s91, -v105
	v_fmac_f32_e32 v105, 0x3377d1cf, v101
	v_fmac_f32_e32 v105, 0x3f317217, v101
	v_cmp_lt_f32_e64 s[0:1], |v101|, s96
	s_nop 1
	v_cndmask_b32_e64 v101, v101, v105, s[0:1]
	v_cndmask_b32_e32 v105, 0, v167, vcc
	v_sub_f32_e32 v101, v101, v105
	v_sub_f32_e32 v101, v104, v101
	v_min_f32_e32 v104, 0, v97
	v_mul_f32_e64 v97, |v97|, s49
	v_exp_f32_e32 v97, v97
	v_add_f32_e32 v101, -0.5, v101
	v_add_f32_e32 v97, 1.0, v97
	v_cmp_gt_f32_e32 vcc, s90, v97
	s_nop 1
	v_cndmask_b32_e64 v105, 0, 32, vcc
	v_ldexp_f32 v97, v97, v105
	v_log_f32_e32 v97, v97
	s_nop 0
	v_mul_f32_e32 v105, 0x3f317217, v97
	v_fma_f32 v105, v97, s91, -v105
	v_fmac_f32_e32 v105, 0x3377d1cf, v97
	v_fmac_f32_e32 v105, 0x3f317217, v97
	v_cmp_lt_f32_e64 s[0:1], |v97|, s96
	s_nop 1
	v_cndmask_b32_e64 v97, v97, v105, s[0:1]
	v_cndmask_b32_e32 v105, 0, v167, vcc
	v_sub_f32_e32 v97, v97, v105
	v_sub_f32_e32 v97, v104, v97
	v_add_f32_e32 v104, -0.5, v97
	v_mul_f32_e32 v97, 0x3fb8aa3b, v101
	v_mul_f32_e32 v101, 0x3fb8aa3b, v104
	v_min_f32_e32 v104, 0, v102
	v_mul_f32_e64 v102, |v102|, s49
	v_exp_f32_e32 v102, v102
	v_exp_f32_e32 v97, v97
	v_exp_f32_e32 v101, v101
	v_add_f32_e32 v102, 1.0, v102
	v_cmp_gt_f32_e32 vcc, s90, v102
	v_mul_f32_e32 v97, 0xbfb8aa3b, v97
	v_exp_f32_e32 v97, v97
	v_cndmask_b32_e64 v105, 0, 32, vcc
	v_ldexp_f32 v102, v102, v105
	v_log_f32_e32 v102, v102
	v_mul_f32_e32 v101, 0xbfb8aa3b, v101
	v_exp_f32_e32 v101, v101
	v_mul_f32_e32 v105, 0x3f317217, v102
	v_fma_f32 v105, v102, s91, -v105
	v_fmac_f32_e32 v105, 0x3377d1cf, v102
	v_fmac_f32_e32 v105, 0x3f317217, v102
	v_cmp_lt_f32_e64 s[0:1], |v102|, s96
	s_nop 1
	v_cndmask_b32_e64 v102, v102, v105, s[0:1]
	v_cndmask_b32_e32 v105, 0, v167, vcc
	v_sub_f32_e32 v102, v102, v105
	v_sub_f32_e32 v102, v104, v102
	v_min_f32_e32 v104, 0, v98
	v_mul_f32_e64 v98, |v98|, s49
	v_exp_f32_e32 v98, v98
	v_add_f32_e32 v102, -0.5, v102
	v_add_f32_e32 v98, 1.0, v98
	v_cmp_gt_f32_e32 vcc, s90, v98
	s_nop 1
	v_cndmask_b32_e64 v105, 0, 32, vcc
	v_ldexp_f32 v98, v98, v105
	v_log_f32_e32 v98, v98
	s_nop 0
	v_mul_f32_e32 v105, 0x3f317217, v98
	v_fma_f32 v105, v98, s91, -v105
	v_fmac_f32_e32 v105, 0x3377d1cf, v98
	v_fmac_f32_e32 v105, 0x3f317217, v98
	v_cmp_lt_f32_e64 s[0:1], |v98|, s96
	s_nop 1
	v_cndmask_b32_e64 v98, v98, v105, s[0:1]
	v_cndmask_b32_e32 v105, 0, v167, vcc
	v_sub_f32_e32 v98, v98, v105
	v_sub_f32_e32 v98, v104, v98
	v_add_f32_e32 v104, -0.5, v98
	v_mul_f32_e32 v98, 0x3fb8aa3b, v102
	v_mul_f32_e32 v102, 0x3fb8aa3b, v104
	v_min_f32_e32 v104, 0, v103
	v_mul_f32_e64 v103, |v103|, s49
	v_exp_f32_e32 v103, v103
	v_exp_f32_e32 v98, v98
	v_exp_f32_e32 v102, v102
	v_add_f32_e32 v103, 1.0, v103
	v_cmp_gt_f32_e32 vcc, s90, v103
	v_mul_f32_e32 v98, 0xbfb8aa3b, v98
	v_exp_f32_e32 v98, v98
	v_cndmask_b32_e64 v105, 0, 32, vcc
	v_ldexp_f32 v103, v103, v105
	v_log_f32_e32 v103, v103
	v_mul_f32_e32 v102, 0xbfb8aa3b, v102
	v_exp_f32_e32 v102, v102
	v_mul_f32_e32 v105, 0x3f317217, v103
	v_fma_f32 v105, v103, s91, -v105
	v_fmac_f32_e32 v105, 0x3377d1cf, v103
	v_fmac_f32_e32 v105, 0x3f317217, v103
	v_cmp_lt_f32_e64 s[0:1], |v103|, s96
	s_nop 1
	v_cndmask_b32_e64 v103, v103, v105, s[0:1]
	v_cndmask_b32_e32 v105, 0, v167, vcc
	v_sub_f32_e32 v103, v103, v105
	v_sub_f32_e32 v103, v104, v103
	v_min_f32_e32 v104, 0, v99
	v_mul_f32_e64 v99, |v99|, s49
	v_exp_f32_e32 v99, v99
	v_add_f32_e32 v103, -0.5, v103
	v_add_f32_e32 v99, 1.0, v99
	v_cmp_gt_f32_e32 vcc, s90, v99
	s_nop 1
	v_cndmask_b32_e64 v105, 0, 32, vcc
	v_ldexp_f32 v99, v99, v105
	v_log_f32_e32 v99, v99
	s_nop 0
	v_mul_f32_e32 v105, 0x3f317217, v99
	v_fma_f32 v105, v99, s91, -v105
	v_fmac_f32_e32 v105, 0x3377d1cf, v99
	v_fmac_f32_e32 v105, 0x3f317217, v99
	v_cmp_lt_f32_e64 s[0:1], |v99|, s96
	s_nop 1
	v_cndmask_b32_e64 v99, v99, v105, s[0:1]
	v_cndmask_b32_e32 v105, 0, v167, vcc
	v_sub_f32_e32 v99, v99, v105
	v_sub_f32_e32 v99, v104, v99
	v_add_f32_e32 v104, -0.5, v99
	v_mul_f32_e32 v99, 0x3fb8aa3b, v103
	v_exp_f32_e32 v99, v99
	v_mul_f32_e32 v103, 0x3fb8aa3b, v104
	v_exp_f32_e32 v103, v103
	v_mul_f32_e32 v99, 0xbfb8aa3b, v99
	v_exp_f32_e32 v99, v99
	v_mul_f32_e32 v103, 0xbfb8aa3b, v103
	v_exp_f32_e32 v103, v103
	global_store_dwordx4 v[112:113], v[96:99], off offset:512
	global_store_dwordx4 v[112:113], v[100:103], off offset:528
	s_or_b64 exec, exec, s[34:35]
	v_cmp_gt_i32_e32 vcc, s38, v152
	s_and_saveexec_b64 s[34:35], vcc
	s_cbranch_execnz .LBB0_803

.LBB0_811:
	v_readlane_b32 s68, v239, 33
	v_lshlrev_b64 v[90:91], 2, v[154:155]
	v_readlane_b32 s70, v239, 35
	v_readlane_b32 s71, v239, 36
	v_or_b32_e32 v88, 48, v152
	v_ashrrev_i32_e32 v89, 31, v88
	v_lshl_add_u64 v[92:93], s[70:71], 0, v[90:91]
	s_nop 1
	v_mov_b64_e32 v[80:81], v[176:177]
	v_mov_b64_e32 v[82:83], v[178:179]
	s_nop 1
	v_mov_b64_e32 v[84:85], v[172:173]
	v_mov_b64_e32 v[86:87], v[174:175]
	v_readlane_b32 s69, v239, 34
	v_readlane_b32 s72, v239, 37
	v_readlane_b32 s73, v239, 38
	v_readlane_b32 s74, v239, 39
	v_readlane_b32 s75, v239, 40
	v_readlane_b32 s76, v239, 41
	v_readlane_b32 s77, v239, 42
	v_readlane_b32 s78, v239, 43
	v_readlane_b32 s79, v239, 44
	v_readlane_b32 s80, v239, 45
	v_readlane_b32 s81, v239, 46
	v_readlane_b32 s82, v239, 47
	v_readlane_b32 s83, v239, 48
	v_add_f32_e32 v72, v72, v80
	v_add_f32_e32 v76, v76, v84
	v_min_f32_e32 v80, 0, v76
	v_mul_f32_e64 v76, |v76|, s49
	v_exp_f32_e32 v76, v76
	v_add_f32_e32 v77, v77, v85
	v_add_f32_e32 v73, v73, v81
	v_add_f32_e32 v78, v78, v86
	v_add_f32_e32 v76, 1.0, v76
	v_cmp_gt_f32_e32 vcc, s90, v76
	v_add_f32_e32 v74, v74, v82
	v_add_f32_e32 v79, v79, v87
	v_cndmask_b32_e64 v84, 0, 32, vcc
	v_ldexp_f32 v76, v76, v84
	v_log_f32_e32 v76, v76
	v_add_f32_e32 v75, v75, v83
	v_mul_f32_e32 v84, 0x3f317217, v76
	v_fma_f32 v84, v76, s91, -v84
	v_fmac_f32_e32 v84, 0x3377d1cf, v76
	v_fmac_f32_e32 v84, 0x3f317217, v76
	v_cmp_lt_f32_e64 s[0:1], |v76|, s96
	s_nop 1
	v_cndmask_b32_e64 v76, v76, v84, s[0:1]
	v_cndmask_b32_e32 v84, 0, v167, vcc
	v_sub_f32_e32 v76, v76, v84
	v_sub_f32_e32 v76, v80, v76
	v_min_f32_e32 v80, 0, v72
	v_mul_f32_e64 v72, |v72|, s49
	v_exp_f32_e32 v72, v72
	v_add_f32_e32 v76, -0.5, v76
	v_mul_f32_e32 v76, 0x3fb8aa3b, v76
	v_exp_f32_e32 v76, v76
	v_add_f32_e32 v72, 1.0, v72
	v_cmp_gt_f32_e32 vcc, s90, v72
	v_mul_f32_e32 v76, 0xbfb8aa3b, v76
	s_nop 0
	v_cndmask_b32_e64 v84, 0, 32, vcc
	v_ldexp_f32 v72, v72, v84
	v_log_f32_e32 v72, v72
	v_exp_f32_e32 v76, v76
	v_mul_f32_e32 v84, 0x3f317217, v72
	v_fma_f32 v84, v72, s91, -v84
	v_fmac_f32_e32 v84, 0x3377d1cf, v72
	v_fmac_f32_e32 v84, 0x3f317217, v72
	v_cmp_lt_f32_e64 s[0:1], |v72|, s96
	s_nop 1
	v_cndmask_b32_e64 v72, v72, v84, s[0:1]
	v_cndmask_b32_e32 v84, 0, v167, vcc
	v_sub_f32_e32 v72, v72, v84
	v_sub_f32_e32 v72, v80, v72
	v_min_f32_e32 v80, 0, v77
	v_mul_f32_e64 v77, |v77|, s49
	v_exp_f32_e32 v77, v77
	v_add_f32_e32 v72, -0.5, v72
	v_mul_f32_e32 v72, 0x3fb8aa3b, v72
	v_exp_f32_e32 v72, v72
	v_add_f32_e32 v77, 1.0, v77
	v_cmp_gt_f32_e32 vcc, s90, v77
	v_mul_f32_e32 v72, 0xbfb8aa3b, v72
	s_nop 0
	v_cndmask_b32_e64 v81, 0, 32, vcc
	v_ldexp_f32 v77, v77, v81
	v_log_f32_e32 v77, v77
	v_exp_f32_e32 v72, v72
	v_mul_f32_e32 v81, 0x3f317217, v77
	v_fma_f32 v81, v77, s91, -v81
	v_fmac_f32_e32 v81, 0x3377d1cf, v77
	v_fmac_f32_e32 v81, 0x3f317217, v77
	v_cmp_lt_f32_e64 s[0:1], |v77|, s96
	s_nop 1
	v_cndmask_b32_e64 v77, v77, v81, s[0:1]
	v_cndmask_b32_e32 v81, 0, v167, vcc
	v_sub_f32_e32 v77, v77, v81
	v_sub_f32_e32 v77, v80, v77
	v_min_f32_e32 v80, 0, v73
	v_mul_f32_e64 v73, |v73|, s49
	v_exp_f32_e32 v73, v73
	v_add_f32_e32 v77, -0.5, v77
	v_mul_f32_e32 v77, 0x3fb8aa3b, v77
	v_exp_f32_e32 v77, v77
	v_add_f32_e32 v73, 1.0, v73
	v_cmp_gt_f32_e32 vcc, s90, v73
	v_mul_f32_e32 v77, 0xbfb8aa3b, v77
	s_nop 0
	v_cndmask_b32_e64 v81, 0, 32, vcc
	v_ldexp_f32 v73, v73, v81
	v_log_f32_e32 v73, v73
	v_exp_f32_e32 v77, v77
	v_mul_f32_e32 v81, 0x3f317217, v73
	v_fma_f32 v81, v73, s91, -v81
	v_fmac_f32_e32 v81, 0x3377d1cf, v73
	v_fmac_f32_e32 v81, 0x3f317217, v73
	v_cmp_lt_f32_e64 s[0:1], |v73|, s96
	s_nop 1
	v_cndmask_b32_e64 v73, v73, v81, s[0:1]
	v_cndmask_b32_e32 v81, 0, v167, vcc
	v_sub_f32_e32 v73, v73, v81
	v_sub_f32_e32 v73, v80, v73
	v_min_f32_e32 v80, 0, v78
	v_mul_f32_e64 v78, |v78|, s49
	v_exp_f32_e32 v78, v78
	v_add_f32_e32 v73, -0.5, v73
	v_mul_f32_e32 v73, 0x3fb8aa3b, v73
	v_exp_f32_e32 v73, v73
	v_add_f32_e32 v78, 1.0, v78
	v_cmp_gt_f32_e32 vcc, s90, v78
	v_mul_f32_e32 v73, 0xbfb8aa3b, v73
	s_nop 0
	v_cndmask_b32_e64 v81, 0, 32, vcc
	v_ldexp_f32 v78, v78, v81
	v_log_f32_e32 v78, v78
	v_exp_f32_e32 v73, v73
	v_mul_f32_e32 v81, 0x3f317217, v78
	v_fma_f32 v81, v78, s91, -v81
	v_fmac_f32_e32 v81, 0x3377d1cf, v78
	v_fmac_f32_e32 v81, 0x3f317217, v78
	v_cmp_lt_f32_e64 s[0:1], |v78|, s96
	s_nop 1
	v_cndmask_b32_e64 v78, v78, v81, s[0:1]
	v_cndmask_b32_e32 v81, 0, v167, vcc
	v_sub_f32_e32 v78, v78, v81
	v_sub_f32_e32 v78, v80, v78
	v_min_f32_e32 v80, 0, v74
	v_mul_f32_e64 v74, |v74|, s49
	v_exp_f32_e32 v74, v74
	v_add_f32_e32 v78, -0.5, v78
	v_mul_f32_e32 v78, 0x3fb8aa3b, v78
	v_exp_f32_e32 v78, v78
	v_add_f32_e32 v74, 1.0, v74
	v_cmp_gt_f32_e32 vcc, s90, v74
	v_mul_f32_e32 v78, 0xbfb8aa3b, v78
	s_nop 0
	v_cndmask_b32_e64 v81, 0, 32, vcc
	v_ldexp_f32 v74, v74, v81
	v_log_f32_e32 v74, v74
	v_exp_f32_e32 v78, v78
	v_mul_f32_e32 v81, 0x3f317217, v74
	v_fma_f32 v81, v74, s91, -v81
	v_fmac_f32_e32 v81, 0x3377d1cf, v74
	v_fmac_f32_e32 v81, 0x3f317217, v74
	v_cmp_lt_f32_e64 s[0:1], |v74|, s96
	s_nop 1
	v_cndmask_b32_e64 v74, v74, v81, s[0:1]
	v_cndmask_b32_e32 v81, 0, v167, vcc
	v_sub_f32_e32 v74, v74, v81
	v_sub_f32_e32 v74, v80, v74
	v_min_f32_e32 v80, 0, v79
	v_mul_f32_e64 v79, |v79|, s49
	v_exp_f32_e32 v79, v79
	v_add_f32_e32 v74, -0.5, v74
	v_mul_f32_e32 v74, 0x3fb8aa3b, v74
	v_exp_f32_e32 v74, v74
	v_add_f32_e32 v79, 1.0, v79
	v_cmp_gt_f32_e32 vcc, s90, v79
	v_mul_f32_e32 v74, 0xbfb8aa3b, v74
	s_nop 0
	v_cndmask_b32_e64 v81, 0, 32, vcc
	v_ldexp_f32 v79, v79, v81
	v_log_f32_e32 v79, v79
	v_exp_f32_e32 v74, v74
	v_mul_f32_e32 v81, 0x3f317217, v79
	v_fma_f32 v81, v79, s91, -v81
	v_fmac_f32_e32 v81, 0x3377d1cf, v79
	v_fmac_f32_e32 v81, 0x3f317217, v79
	v_cmp_lt_f32_e64 s[0:1], |v79|, s96
	s_nop 1
	v_cndmask_b32_e64 v79, v79, v81, s[0:1]
	v_cndmask_b32_e32 v81, 0, v167, vcc
	v_sub_f32_e32 v79, v79, v81
	v_sub_f32_e32 v79, v80, v79
	v_min_f32_e32 v80, 0, v75
	v_mul_f32_e64 v75, |v75|, s49
	v_exp_f32_e32 v75, v75
	v_add_f32_e32 v79, -0.5, v79
	v_mul_f32_e32 v79, 0x3fb8aa3b, v79
	v_exp_f32_e32 v79, v79
	v_add_f32_e32 v75, 1.0, v75
	v_cmp_gt_f32_e32 vcc, s90, v75
	v_mul_f32_e32 v79, 0xbfb8aa3b, v79
	s_nop 0
	v_cndmask_b32_e64 v81, 0, 32, vcc
	v_ldexp_f32 v75, v75, v81
	v_log_f32_e32 v75, v75
	v_exp_f32_e32 v79, v79
	v_mul_f32_e32 v81, 0x3f317217, v75
	v_fma_f32 v81, v75, s91, -v81
	v_fmac_f32_e32 v81, 0x3377d1cf, v75
	v_fmac_f32_e32 v81, 0x3f317217, v75
	v_cmp_lt_f32_e64 s[0:1], |v75|, s96
	s_nop 1
	v_cndmask_b32_e64 v75, v75, v81, s[0:1]
	v_cndmask_b32_e32 v81, 0, v167, vcc
	v_sub_f32_e32 v75, v75, v81
	v_sub_f32_e32 v75, v80, v75
	v_add_f32_e32 v75, -0.5, v75
	v_mul_f32_e32 v75, 0x3fb8aa3b, v75
	v_exp_f32_e32 v75, v75
	v_lshlrev_b64 v[80:81], 12, v[88:89]
	v_lshl_add_u64 v[80:81], s[10:11], 0, v[80:81]
	v_lshl_add_u64 v[80:81], v[80:81], 0, v[90:91]
	v_mul_f32_e32 v75, 0xbfb8aa3b, v75
	v_exp_f32_e32 v75, v75
	global_store_dwordx4 v[80:81], v[76:79], off
	global_store_dwordx4 v[80:81], v[72:75], off offset:16
	s_nop 1
	v_mov_b64_e32 v[72:73], v[184:185]
	v_mov_b64_e32 v[74:75], v[186:187]
	s_nop 0
	s_nop 1
	v_mov_b64_e32 v[76:77], v[180:181]
	v_mov_b64_e32 v[78:79], v[182:183]
	v_add_f32_e32 v64, v64, v72
	v_add_f32_e32 v68, v68, v76
	v_min_f32_e32 v72, 0, v68
	v_mul_f32_e64 v68, |v68|, s49
	v_exp_f32_e32 v68, v68
	v_add_f32_e32 v69, v69, v77
	v_add_f32_e32 v65, v65, v73
	v_add_f32_e32 v70, v70, v78
	v_add_f32_e32 v68, 1.0, v68
	v_cmp_gt_f32_e32 vcc, s90, v68
	v_add_f32_e32 v66, v66, v74
	v_add_f32_e32 v71, v71, v79
	v_cndmask_b32_e64 v76, 0, 32, vcc
	v_ldexp_f32 v68, v68, v76
	v_log_f32_e32 v68, v68
	v_add_f32_e32 v67, v67, v75
	v_mul_f32_e32 v76, 0x3f317217, v68
	v_fma_f32 v76, v68, s91, -v76
	v_fmac_f32_e32 v76, 0x3377d1cf, v68
	v_fmac_f32_e32 v76, 0x3f317217, v68
	v_cmp_lt_f32_e64 s[0:1], |v68|, s96
	s_nop 1
	v_cndmask_b32_e64 v68, v68, v76, s[0:1]
	v_cndmask_b32_e32 v76, 0, v167, vcc
	v_sub_f32_e32 v68, v68, v76
	v_sub_f32_e32 v68, v72, v68
	v_min_f32_e32 v72, 0, v64
	v_mul_f32_e64 v64, |v64|, s49
	v_exp_f32_e32 v64, v64
	v_add_f32_e32 v68, -0.5, v68
	v_add_f32_e32 v64, 1.0, v64
	v_cmp_gt_f32_e32 vcc, s90, v64
	s_nop 1
	v_cndmask_b32_e64 v76, 0, 32, vcc
	v_ldexp_f32 v64, v64, v76
	v_log_f32_e32 v64, v64
	s_nop 0
	v_mul_f32_e32 v76, 0x3f317217, v64
	v_fma_f32 v76, v64, s91, -v76
	v_fmac_f32_e32 v76, 0x3377d1cf, v64
	v_fmac_f32_e32 v76, 0x3f317217, v64
	v_cmp_lt_f32_e64 s[0:1], |v64|, s96
	s_nop 1
	v_cndmask_b32_e64 v64, v64, v76, s[0:1]
	v_cndmask_b32_e32 v76, 0, v167, vcc
	v_sub_f32_e32 v64, v64, v76
	v_sub_f32_e32 v64, v72, v64
	v_add_f32_e32 v72, -0.5, v64
	v_mul_f32_e32 v64, 0x3fb8aa3b, v68
	v_mul_f32_e32 v68, 0x3fb8aa3b, v72
	v_min_f32_e32 v72, 0, v69
	v_mul_f32_e64 v69, |v69|, s49
	v_exp_f32_e32 v69, v69
	v_exp_f32_e32 v64, v64
	v_exp_f32_e32 v68, v68
	v_add_f32_e32 v69, 1.0, v69
	v_cmp_gt_f32_e32 vcc, s90, v69
	v_mul_f32_e32 v64, 0xbfb8aa3b, v64
	v_exp_f32_e32 v64, v64
	v_cndmask_b32_e64 v73, 0, 32, vcc
	v_ldexp_f32 v69, v69, v73
	v_log_f32_e32 v69, v69
	v_mul_f32_e32 v68, 0xbfb8aa3b, v68
	v_exp_f32_e32 v68, v68
	v_mul_f32_e32 v73, 0x3f317217, v69
	v_fma_f32 v73, v69, s91, -v73
	v_fmac_f32_e32 v73, 0x3377d1cf, v69
	v_fmac_f32_e32 v73, 0x3f317217, v69
	v_cmp_lt_f32_e64 s[0:1], |v69|, s96
	s_nop 1
	v_cndmask_b32_e64 v69, v69, v73, s[0:1]
	v_cndmask_b32_e32 v73, 0, v167, vcc
	v_sub_f32_e32 v69, v69, v73
	v_sub_f32_e32 v69, v72, v69
	v_min_f32_e32 v72, 0, v65
	v_mul_f32_e64 v65, |v65|, s49
	v_exp_f32_e32 v65, v65
	v_add_f32_e32 v69, -0.5, v69
	v_add_f32_e32 v65, 1.0, v65
	v_cmp_gt_f32_e32 vcc, s90, v65
	s_nop 1
	v_cndmask_b32_e64 v73, 0, 32, vcc
	v_ldexp_f32 v65, v65, v73
	v_log_f32_e32 v65, v65
	s_nop 0
	v_mul_f32_e32 v73, 0x3f317217, v65
	v_fma_f32 v73, v65, s91, -v73
	v_fmac_f32_e32 v73, 0x3377d1cf, v65
	v_fmac_f32_e32 v73, 0x3f317217, v65
	v_cmp_lt_f32_e64 s[0:1], |v65|, s96
	s_nop 1
	v_cndmask_b32_e64 v65, v65, v73, s[0:1]
	v_cndmask_b32_e32 v73, 0, v167, vcc
	v_sub_f32_e32 v65, v65, v73
	v_sub_f32_e32 v65, v72, v65
	v_add_f32_e32 v72, -0.5, v65
	v_mul_f32_e32 v65, 0x3fb8aa3b, v69
	v_mul_f32_e32 v69, 0x3fb8aa3b, v72
	v_min_f32_e32 v72, 0, v70
	v_mul_f32_e64 v70, |v70|, s49
	v_exp_f32_e32 v70, v70
	v_exp_f32_e32 v65, v65
	v_exp_f32_e32 v69, v69
	v_add_f32_e32 v70, 1.0, v70
	v_cmp_gt_f32_e32 vcc, s90, v70
	v_mul_f32_e32 v65, 0xbfb8aa3b, v65
	v_exp_f32_e32 v65, v65
	v_cndmask_b32_e64 v73, 0, 32, vcc
	v_ldexp_f32 v70, v70, v73
	v_log_f32_e32 v70, v70
	v_mul_f32_e32 v69, 0xbfb8aa3b, v69
	v_exp_f32_e32 v69, v69
	v_mul_f32_e32 v73, 0x3f317217, v70
	v_fma_f32 v73, v70, s91, -v73
	v_fmac_f32_e32 v73, 0x3377d1cf, v70
	v_fmac_f32_e32 v73, 0x3f317217, v70
	v_cmp_lt_f32_e64 s[0:1], |v70|, s96
	s_nop 1
	v_cndmask_b32_e64 v70, v70, v73, s[0:1]
	v_cndmask_b32_e32 v73, 0, v167, vcc
	v_sub_f32_e32 v70, v70, v73
	v_sub_f32_e32 v70, v72, v70
	v_min_f32_e32 v72, 0, v66
	v_mul_f32_e64 v66, |v66|, s49
	v_exp_f32_e32 v66, v66
	v_add_f32_e32 v70, -0.5, v70
	v_add_f32_e32 v66, 1.0, v66
	v_cmp_gt_f32_e32 vcc, s90, v66
	s_nop 1
	v_cndmask_b32_e64 v73, 0, 32, vcc
	v_ldexp_f32 v66, v66, v73
	v_log_f32_e32 v66, v66
	s_nop 0
	v_mul_f32_e32 v73, 0x3f317217, v66
	v_fma_f32 v73, v66, s91, -v73
	v_fmac_f32_e32 v73, 0x3377d1cf, v66
	v_fmac_f32_e32 v73, 0x3f317217, v66
	v_cmp_lt_f32_e64 s[0:1], |v66|, s96
	s_nop 1
	v_cndmask_b32_e64 v66, v66, v73, s[0:1]
	v_cndmask_b32_e32 v73, 0, v167, vcc
	v_sub_f32_e32 v66, v66, v73
	v_sub_f32_e32 v66, v72, v66
	v_add_f32_e32 v72, -0.5, v66
	v_mul_f32_e32 v66, 0x3fb8aa3b, v70
	v_mul_f32_e32 v70, 0x3fb8aa3b, v72
	v_min_f32_e32 v72, 0, v71
	v_mul_f32_e64 v71, |v71|, s49
	v_exp_f32_e32 v71, v71
	v_exp_f32_e32 v66, v66
	v_exp_f32_e32 v70, v70
	v_add_f32_e32 v71, 1.0, v71
	v_cmp_gt_f32_e32 vcc, s90, v71
	v_mul_f32_e32 v66, 0xbfb8aa3b, v66
	v_exp_f32_e32 v66, v66
	v_cndmask_b32_e64 v73, 0, 32, vcc
	v_ldexp_f32 v71, v71, v73
	v_log_f32_e32 v71, v71
	v_mul_f32_e32 v70, 0xbfb8aa3b, v70
	v_exp_f32_e32 v70, v70
	v_mul_f32_e32 v73, 0x3f317217, v71
	v_fma_f32 v73, v71, s91, -v73
	v_fmac_f32_e32 v73, 0x3377d1cf, v71
	v_fmac_f32_e32 v73, 0x3f317217, v71
	v_cmp_lt_f32_e64 s[0:1], |v71|, s96
	s_nop 1
	v_cndmask_b32_e64 v71, v71, v73, s[0:1]
	v_cndmask_b32_e32 v73, 0, v167, vcc
	v_sub_f32_e32 v71, v71, v73
	v_sub_f32_e32 v71, v72, v71
	v_min_f32_e32 v72, 0, v67
	v_mul_f32_e64 v67, |v67|, s49
	v_exp_f32_e32 v67, v67
	v_add_f32_e32 v71, -0.5, v71
	v_add_f32_e32 v67, 1.0, v67
	v_cmp_gt_f32_e32 vcc, s90, v67
	s_nop 1
	v_cndmask_b32_e64 v73, 0, 32, vcc
	v_ldexp_f32 v67, v67, v73
	v_log_f32_e32 v67, v67
	s_nop 0
	v_mul_f32_e32 v73, 0x3f317217, v67
	v_fma_f32 v73, v67, s91, -v73
	v_fmac_f32_e32 v73, 0x3377d1cf, v67
	v_fmac_f32_e32 v73, 0x3f317217, v67
	v_cmp_lt_f32_e64 s[0:1], |v67|, s96
	s_nop 1
	v_cndmask_b32_e64 v67, v67, v73, s[0:1]
	v_cndmask_b32_e32 v73, 0, v167, vcc
	v_sub_f32_e32 v67, v67, v73
	v_sub_f32_e32 v67, v72, v67
	v_add_f32_e32 v72, -0.5, v67
	v_mul_f32_e32 v67, 0x3fb8aa3b, v71
	v_exp_f32_e32 v67, v67
	v_mul_f32_e32 v71, 0x3fb8aa3b, v72
	v_exp_f32_e32 v71, v71
	v_mul_f32_e32 v67, 0xbfb8aa3b, v67
	v_exp_f32_e32 v67, v67
	v_mul_f32_e32 v71, 0xbfb8aa3b, v71
	v_exp_f32_e32 v71, v71
	global_store_dwordx4 v[80:81], v[64:67], off offset:512
	global_store_dwordx4 v[80:81], v[68:71], off offset:528
	s_or_b64 exec, exec, s[34:35]
	v_cmp_gt_i32_e32 vcc, s60, v152
	s_and_saveexec_b64 s[34:35], vcc
	s_cbranch_execnz .LBB0_805

.LBB0_813:
	v_readlane_b32 s68, v239, 33
	v_lshlrev_b64 v[58:59], 2, v[154:155]
	v_readlane_b32 s70, v239, 35
	v_readlane_b32 s71, v239, 36
	v_readlane_b32 s69, v239, 34
	v_readlane_b32 s72, v239, 37
	v_lshl_add_u64 v[56:57], s[70:71], 0, v[58:59]
	s_nop 1
	v_mov_b64_e32 v[48:49], v[176:177]
	v_mov_b64_e32 v[50:51], v[178:179]
	s_nop 1
	v_mov_b64_e32 v[52:53], v[172:173]
	v_mov_b64_e32 v[54:55], v[174:175]
	v_readlane_b32 s73, v239, 38
	v_readlane_b32 s74, v239, 39
	v_readlane_b32 s75, v239, 40
	v_readlane_b32 s76, v239, 41
	v_readlane_b32 s77, v239, 42
	v_readlane_b32 s78, v239, 43
	v_readlane_b32 s79, v239, 44
	v_readlane_b32 s80, v239, 45
	v_readlane_b32 s81, v239, 46
	v_readlane_b32 s82, v239, 47
	v_readlane_b32 s83, v239, 48
	v_add_f32_e32 v40, v40, v48
	v_add_f32_e32 v44, v44, v52
	v_min_f32_e32 v48, 0, v44
	v_mul_f32_e64 v44, |v44|, s49
	v_exp_f32_e32 v44, v44
	v_add_f32_e32 v45, v45, v53
	v_add_f32_e32 v41, v41, v49
	v_add_f32_e32 v46, v46, v54
	v_add_f32_e32 v44, 1.0, v44
	v_cmp_gt_f32_e32 vcc, s90, v44
	v_add_f32_e32 v42, v42, v50
	v_add_f32_e32 v47, v47, v55
	v_cndmask_b32_e64 v52, 0, 32, vcc
	v_ldexp_f32 v44, v44, v52
	v_log_f32_e32 v44, v44
	v_add_f32_e32 v43, v43, v51
	v_mul_f32_e32 v52, 0x3f317217, v44
	v_fma_f32 v52, v44, s91, -v52
	v_fmac_f32_e32 v52, 0x3377d1cf, v44
	v_fmac_f32_e32 v52, 0x3f317217, v44
	v_cmp_lt_f32_e64 s[0:1], |v44|, s96
	s_nop 1
	v_cndmask_b32_e64 v44, v44, v52, s[0:1]
	v_cndmask_b32_e32 v52, 0, v167, vcc
	v_sub_f32_e32 v44, v44, v52
	v_sub_f32_e32 v44, v48, v44
	v_min_f32_e32 v48, 0, v40
	v_mul_f32_e64 v40, |v40|, s49
	v_exp_f32_e32 v40, v40
	v_add_f32_e32 v44, -0.5, v44
	v_mul_f32_e32 v44, 0x3fb8aa3b, v44
	v_exp_f32_e32 v44, v44
	v_add_f32_e32 v40, 1.0, v40
	v_cmp_gt_f32_e32 vcc, s90, v40
	v_mul_f32_e32 v44, 0xbfb8aa3b, v44
	s_nop 0
	v_cndmask_b32_e64 v52, 0, 32, vcc
	v_ldexp_f32 v40, v40, v52
	v_log_f32_e32 v40, v40
	v_exp_f32_e32 v44, v44
	v_mul_f32_e32 v52, 0x3f317217, v40
	v_fma_f32 v52, v40, s91, -v52
	v_fmac_f32_e32 v52, 0x3377d1cf, v40
	v_fmac_f32_e32 v52, 0x3f317217, v40
	v_cmp_lt_f32_e64 s[0:1], |v40|, s96
	s_nop 1
	v_cndmask_b32_e64 v40, v40, v52, s[0:1]
	v_cndmask_b32_e32 v52, 0, v167, vcc
	v_sub_f32_e32 v40, v40, v52
	v_sub_f32_e32 v40, v48, v40
	v_min_f32_e32 v48, 0, v45
	v_mul_f32_e64 v45, |v45|, s49
	v_exp_f32_e32 v45, v45
	v_add_f32_e32 v40, -0.5, v40
	v_mul_f32_e32 v40, 0x3fb8aa3b, v40
	v_exp_f32_e32 v40, v40
	v_add_f32_e32 v45, 1.0, v45
	v_cmp_gt_f32_e32 vcc, s90, v45
	v_mul_f32_e32 v40, 0xbfb8aa3b, v40
	s_nop 0
	v_cndmask_b32_e64 v49, 0, 32, vcc
	v_ldexp_f32 v45, v45, v49
	v_log_f32_e32 v45, v45
	v_exp_f32_e32 v40, v40
	v_mul_f32_e32 v49, 0x3f317217, v45
	v_fma_f32 v49, v45, s91, -v49
	v_fmac_f32_e32 v49, 0x3377d1cf, v45
	v_fmac_f32_e32 v49, 0x3f317217, v45
	v_cmp_lt_f32_e64 s[0:1], |v45|, s96
	s_nop 1
	v_cndmask_b32_e64 v45, v45, v49, s[0:1]
	v_cndmask_b32_e32 v49, 0, v167, vcc
	v_sub_f32_e32 v45, v45, v49
	v_sub_f32_e32 v45, v48, v45
	v_min_f32_e32 v48, 0, v41
	v_mul_f32_e64 v41, |v41|, s49
	v_exp_f32_e32 v41, v41
	v_add_f32_e32 v45, -0.5, v45
	v_mul_f32_e32 v45, 0x3fb8aa3b, v45
	v_exp_f32_e32 v45, v45
	v_add_f32_e32 v41, 1.0, v41
	v_cmp_gt_f32_e32 vcc, s90, v41
	v_mul_f32_e32 v45, 0xbfb8aa3b, v45
	s_nop 0
	v_cndmask_b32_e64 v49, 0, 32, vcc
	v_ldexp_f32 v41, v41, v49
	v_log_f32_e32 v41, v41
	v_exp_f32_e32 v45, v45
	v_mul_f32_e32 v49, 0x3f317217, v41
	v_fma_f32 v49, v41, s91, -v49
	v_fmac_f32_e32 v49, 0x3377d1cf, v41
	v_fmac_f32_e32 v49, 0x3f317217, v41
	v_cmp_lt_f32_e64 s[0:1], |v41|, s96
	s_nop 1
	v_cndmask_b32_e64 v41, v41, v49, s[0:1]
	v_cndmask_b32_e32 v49, 0, v167, vcc
	v_sub_f32_e32 v41, v41, v49
	v_sub_f32_e32 v41, v48, v41
	v_min_f32_e32 v48, 0, v46
	v_mul_f32_e64 v46, |v46|, s49
	v_exp_f32_e32 v46, v46
	v_add_f32_e32 v41, -0.5, v41
	v_mul_f32_e32 v41, 0x3fb8aa3b, v41
	v_exp_f32_e32 v41, v41
	v_add_f32_e32 v46, 1.0, v46
	v_cmp_gt_f32_e32 vcc, s90, v46
	v_mul_f32_e32 v41, 0xbfb8aa3b, v41
	s_nop 0
	v_cndmask_b32_e64 v49, 0, 32, vcc
	v_ldexp_f32 v46, v46, v49
	v_log_f32_e32 v46, v46
	v_exp_f32_e32 v41, v41
	v_mul_f32_e32 v49, 0x3f317217, v46
	v_fma_f32 v49, v46, s91, -v49
	v_fmac_f32_e32 v49, 0x3377d1cf, v46
	v_fmac_f32_e32 v49, 0x3f317217, v46
	v_cmp_lt_f32_e64 s[0:1], |v46|, s96
	s_nop 1
	v_cndmask_b32_e64 v46, v46, v49, s[0:1]
	v_cndmask_b32_e32 v49, 0, v167, vcc
	v_sub_f32_e32 v46, v46, v49
	v_sub_f32_e32 v46, v48, v46
	v_min_f32_e32 v48, 0, v42
	v_mul_f32_e64 v42, |v42|, s49
	v_exp_f32_e32 v42, v42
	v_add_f32_e32 v46, -0.5, v46
	v_mul_f32_e32 v46, 0x3fb8aa3b, v46
	v_exp_f32_e32 v46, v46
	v_add_f32_e32 v42, 1.0, v42
	v_cmp_gt_f32_e32 vcc, s90, v42
	v_mul_f32_e32 v46, 0xbfb8aa3b, v46
	s_nop 0
	v_cndmask_b32_e64 v49, 0, 32, vcc
	v_ldexp_f32 v42, v42, v49
	v_log_f32_e32 v42, v42
	v_exp_f32_e32 v46, v46
	v_mul_f32_e32 v49, 0x3f317217, v42
	v_fma_f32 v49, v42, s91, -v49
	v_fmac_f32_e32 v49, 0x3377d1cf, v42
	v_fmac_f32_e32 v49, 0x3f317217, v42
	v_cmp_lt_f32_e64 s[0:1], |v42|, s96
	s_nop 1
	v_cndmask_b32_e64 v42, v42, v49, s[0:1]
	v_cndmask_b32_e32 v49, 0, v167, vcc
	v_sub_f32_e32 v42, v42, v49
	v_sub_f32_e32 v42, v48, v42
	v_min_f32_e32 v48, 0, v47
	v_mul_f32_e64 v47, |v47|, s49
	v_exp_f32_e32 v47, v47
	v_add_f32_e32 v42, -0.5, v42
	v_mul_f32_e32 v42, 0x3fb8aa3b, v42
	v_exp_f32_e32 v42, v42
	v_add_f32_e32 v47, 1.0, v47
	v_cmp_gt_f32_e32 vcc, s90, v47
	v_mul_f32_e32 v42, 0xbfb8aa3b, v42
	s_nop 0
	v_cndmask_b32_e64 v49, 0, 32, vcc
	v_ldexp_f32 v47, v47, v49
	v_log_f32_e32 v47, v47
	v_exp_f32_e32 v42, v42
	v_mul_f32_e32 v49, 0x3f317217, v47
	v_fma_f32 v49, v47, s91, -v49
	v_fmac_f32_e32 v49, 0x3377d1cf, v47
	v_fmac_f32_e32 v49, 0x3f317217, v47
	v_cmp_lt_f32_e64 s[0:1], |v47|, s96
	s_nop 1
	v_cndmask_b32_e64 v47, v47, v49, s[0:1]
	v_cndmask_b32_e32 v49, 0, v167, vcc
	v_sub_f32_e32 v47, v47, v49
	v_sub_f32_e32 v47, v48, v47
	v_min_f32_e32 v48, 0, v43
	v_mul_f32_e64 v43, |v43|, s49
	v_exp_f32_e32 v43, v43
	v_add_f32_e32 v47, -0.5, v47
	v_mul_f32_e32 v47, 0x3fb8aa3b, v47
	v_exp_f32_e32 v47, v47
	v_add_f32_e32 v43, 1.0, v43
	v_cmp_gt_f32_e32 vcc, s90, v43
	v_mul_f32_e32 v47, 0xbfb8aa3b, v47
	s_nop 0
	v_cndmask_b32_e64 v49, 0, 32, vcc
	v_ldexp_f32 v43, v43, v49
	v_log_f32_e32 v43, v43
	v_exp_f32_e32 v47, v47
	v_mul_f32_e32 v49, 0x3f317217, v43
	v_fma_f32 v49, v43, s91, -v49
	v_fmac_f32_e32 v49, 0x3377d1cf, v43
	v_fmac_f32_e32 v49, 0x3f317217, v43
	v_cmp_lt_f32_e64 s[0:1], |v43|, s96
	s_nop 1
	v_cndmask_b32_e64 v43, v43, v49, s[0:1]
	v_cndmask_b32_e32 v49, 0, v167, vcc
	v_sub_f32_e32 v43, v43, v49
	v_sub_f32_e32 v43, v48, v43
	v_add_f32_e32 v43, -0.5, v43
	v_mul_f32_e32 v43, 0x3fb8aa3b, v43
	v_exp_f32_e32 v43, v43
	v_lshlrev_b64 v[48:49], 12, v[152:153]
	v_lshl_add_u64 v[48:49], s[10:11], 0, v[48:49]
	v_lshl_add_u64 v[50:51], v[48:49], 0, v[58:59]
	v_mul_f32_e32 v43, 0xbfb8aa3b, v43
	s_mov_b64 s[0:1], 0x90000
	v_exp_f32_e32 v43, v43
	v_lshl_add_u64 v[48:49], v[50:51], 0, s[0:1]
	s_mov_b32 s0, 0x90000
	v_add_co_u32_e32 v50, vcc, s0, v50
	s_nop 1
	v_addc_co_u32_e32 v51, vcc, 0, v51, vcc
	global_store_dwordx4 v[50:51], v[44:47], off
	global_store_dwordx4 v[48:49], v[40:43], off offset:16
	s_nop 1
	v_mov_b64_e32 v[40:41], v[184:185]
	v_mov_b64_e32 v[42:43], v[186:187]
	s_nop 0
	s_nop 1
	v_mov_b64_e32 v[44:45], v[180:181]
	v_mov_b64_e32 v[46:47], v[182:183]
	v_add_f32_e32 v32, v32, v40
	v_add_f32_e32 v36, v36, v44
	v_min_f32_e32 v40, 0, v36
	v_mul_f32_e64 v36, |v36|, s49
	v_exp_f32_e32 v36, v36
	v_add_f32_e32 v37, v37, v45
	v_add_f32_e32 v33, v33, v41
	v_add_f32_e32 v38, v38, v46
	v_add_f32_e32 v36, 1.0, v36
	v_cmp_gt_f32_e32 vcc, s90, v36
	v_add_f32_e32 v34, v34, v42
	v_add_f32_e32 v39, v39, v47
	v_cndmask_b32_e64 v44, 0, 32, vcc
	v_ldexp_f32 v36, v36, v44
	v_log_f32_e32 v36, v36
	v_add_f32_e32 v35, v35, v43
	v_mul_f32_e32 v44, 0x3f317217, v36
	v_fma_f32 v44, v36, s91, -v44
	v_fmac_f32_e32 v44, 0x3377d1cf, v36
	v_fmac_f32_e32 v44, 0x3f317217, v36
	v_cmp_lt_f32_e64 s[0:1], |v36|, s96
	s_nop 1
	v_cndmask_b32_e64 v36, v36, v44, s[0:1]
	v_cndmask_b32_e32 v44, 0, v167, vcc
	v_sub_f32_e32 v36, v36, v44
	v_sub_f32_e32 v36, v40, v36
	v_min_f32_e32 v40, 0, v32
	v_mul_f32_e64 v32, |v32|, s49
	v_exp_f32_e32 v32, v32
	v_add_f32_e32 v36, -0.5, v36
	v_add_f32_e32 v32, 1.0, v32
	v_cmp_gt_f32_e32 vcc, s90, v32
	s_nop 1
	v_cndmask_b32_e64 v44, 0, 32, vcc
	v_ldexp_f32 v32, v32, v44
	v_log_f32_e32 v32, v32
	s_nop 0
	v_mul_f32_e32 v44, 0x3f317217, v32
	v_fma_f32 v44, v32, s91, -v44
	v_fmac_f32_e32 v44, 0x3377d1cf, v32
	v_fmac_f32_e32 v44, 0x3f317217, v32
	v_cmp_lt_f32_e64 s[0:1], |v32|, s96
	s_nop 1
	v_cndmask_b32_e64 v32, v32, v44, s[0:1]
	v_cndmask_b32_e32 v44, 0, v167, vcc
	v_sub_f32_e32 v32, v32, v44
	v_sub_f32_e32 v32, v40, v32
	v_add_f32_e32 v40, -0.5, v32
	v_mul_f32_e32 v32, 0x3fb8aa3b, v36
	v_mul_f32_e32 v36, 0x3fb8aa3b, v40
	v_min_f32_e32 v40, 0, v37
	v_mul_f32_e64 v37, |v37|, s49
	v_exp_f32_e32 v37, v37
	v_exp_f32_e32 v32, v32
	v_exp_f32_e32 v36, v36
	v_add_f32_e32 v37, 1.0, v37
	v_cmp_gt_f32_e32 vcc, s90, v37
	v_mul_f32_e32 v32, 0xbfb8aa3b, v32
	v_exp_f32_e32 v32, v32
	v_cndmask_b32_e64 v41, 0, 32, vcc
	v_ldexp_f32 v37, v37, v41
	v_log_f32_e32 v37, v37
	v_mul_f32_e32 v36, 0xbfb8aa3b, v36
	v_exp_f32_e32 v36, v36
	v_mul_f32_e32 v41, 0x3f317217, v37
	v_fma_f32 v41, v37, s91, -v41
	v_fmac_f32_e32 v41, 0x3377d1cf, v37
	v_fmac_f32_e32 v41, 0x3f317217, v37
	v_cmp_lt_f32_e64 s[0:1], |v37|, s96
	s_nop 1
	v_cndmask_b32_e64 v37, v37, v41, s[0:1]
	v_cndmask_b32_e32 v41, 0, v167, vcc
	v_sub_f32_e32 v37, v37, v41
	v_sub_f32_e32 v37, v40, v37
	v_min_f32_e32 v40, 0, v33
	v_mul_f32_e64 v33, |v33|, s49
	v_exp_f32_e32 v33, v33
	v_add_f32_e32 v37, -0.5, v37
	v_add_f32_e32 v33, 1.0, v33
	v_cmp_gt_f32_e32 vcc, s90, v33
	s_nop 1
	v_cndmask_b32_e64 v41, 0, 32, vcc
	v_ldexp_f32 v33, v33, v41
	v_log_f32_e32 v33, v33
	s_nop 0
	v_mul_f32_e32 v41, 0x3f317217, v33
	v_fma_f32 v41, v33, s91, -v41
	v_fmac_f32_e32 v41, 0x3377d1cf, v33
	v_fmac_f32_e32 v41, 0x3f317217, v33
	v_cmp_lt_f32_e64 s[0:1], |v33|, s96
	s_nop 1
	v_cndmask_b32_e64 v33, v33, v41, s[0:1]
	v_cndmask_b32_e32 v41, 0, v167, vcc
	v_sub_f32_e32 v33, v33, v41
	v_sub_f32_e32 v33, v40, v33
	v_add_f32_e32 v40, -0.5, v33
	v_mul_f32_e32 v33, 0x3fb8aa3b, v37
	v_mul_f32_e32 v37, 0x3fb8aa3b, v40
	v_min_f32_e32 v40, 0, v38
	v_mul_f32_e64 v38, |v38|, s49
	v_exp_f32_e32 v38, v38
	v_exp_f32_e32 v33, v33
	v_exp_f32_e32 v37, v37
	v_add_f32_e32 v38, 1.0, v38
	v_cmp_gt_f32_e32 vcc, s90, v38
	v_mul_f32_e32 v33, 0xbfb8aa3b, v33
	v_exp_f32_e32 v33, v33
	v_cndmask_b32_e64 v41, 0, 32, vcc
	v_ldexp_f32 v38, v38, v41
	v_log_f32_e32 v38, v38
	v_mul_f32_e32 v37, 0xbfb8aa3b, v37
	v_exp_f32_e32 v37, v37
	v_mul_f32_e32 v41, 0x3f317217, v38
	v_fma_f32 v41, v38, s91, -v41
	v_fmac_f32_e32 v41, 0x3377d1cf, v38
	v_fmac_f32_e32 v41, 0x3f317217, v38
	v_cmp_lt_f32_e64 s[0:1], |v38|, s96
	s_nop 1
	v_cndmask_b32_e64 v38, v38, v41, s[0:1]
	v_cndmask_b32_e32 v41, 0, v167, vcc
	v_sub_f32_e32 v38, v38, v41
	v_sub_f32_e32 v38, v40, v38
	v_min_f32_e32 v40, 0, v34
	v_mul_f32_e64 v34, |v34|, s49
	v_exp_f32_e32 v34, v34
	v_add_f32_e32 v38, -0.5, v38
	v_add_f32_e32 v34, 1.0, v34
	v_cmp_gt_f32_e32 vcc, s90, v34
	s_nop 1
	v_cndmask_b32_e64 v41, 0, 32, vcc
	v_ldexp_f32 v34, v34, v41
	v_log_f32_e32 v34, v34
	s_nop 0
	v_mul_f32_e32 v41, 0x3f317217, v34
	v_fma_f32 v41, v34, s91, -v41
	v_fmac_f32_e32 v41, 0x3377d1cf, v34
	v_fmac_f32_e32 v41, 0x3f317217, v34
	v_cmp_lt_f32_e64 s[0:1], |v34|, s96
	s_nop 1
	v_cndmask_b32_e64 v34, v34, v41, s[0:1]
	v_cndmask_b32_e32 v41, 0, v167, vcc
	v_sub_f32_e32 v34, v34, v41
	v_sub_f32_e32 v34, v40, v34
	v_add_f32_e32 v40, -0.5, v34
	v_mul_f32_e32 v34, 0x3fb8aa3b, v38
	v_mul_f32_e32 v38, 0x3fb8aa3b, v40
	v_min_f32_e32 v40, 0, v39
	v_mul_f32_e64 v39, |v39|, s49
	v_exp_f32_e32 v39, v39
	v_exp_f32_e32 v34, v34
	v_exp_f32_e32 v38, v38
	v_add_f32_e32 v39, 1.0, v39
	v_cmp_gt_f32_e32 vcc, s90, v39
	v_mul_f32_e32 v34, 0xbfb8aa3b, v34
	v_exp_f32_e32 v34, v34
	v_cndmask_b32_e64 v41, 0, 32, vcc
	v_ldexp_f32 v39, v39, v41
	v_log_f32_e32 v39, v39
	v_mul_f32_e32 v38, 0xbfb8aa3b, v38
	v_exp_f32_e32 v38, v38
	v_mul_f32_e32 v41, 0x3f317217, v39
	v_fma_f32 v41, v39, s91, -v41
	v_fmac_f32_e32 v41, 0x3377d1cf, v39
	v_fmac_f32_e32 v41, 0x3f317217, v39
	v_cmp_lt_f32_e64 s[0:1], |v39|, s96
	s_nop 1
	v_cndmask_b32_e64 v39, v39, v41, s[0:1]
	v_cndmask_b32_e32 v41, 0, v167, vcc
	v_sub_f32_e32 v39, v39, v41
	v_sub_f32_e32 v39, v40, v39
	v_min_f32_e32 v40, 0, v35
	v_mul_f32_e64 v35, |v35|, s49
	v_exp_f32_e32 v35, v35
	v_add_f32_e32 v39, -0.5, v39
	v_add_f32_e32 v35, 1.0, v35
	v_cmp_gt_f32_e32 vcc, s90, v35
	s_nop 1
	v_cndmask_b32_e64 v41, 0, 32, vcc
	v_ldexp_f32 v35, v35, v41
	v_log_f32_e32 v35, v35
	s_nop 0
	v_mul_f32_e32 v41, 0x3f317217, v35
	v_fma_f32 v41, v35, s91, -v41
	v_fmac_f32_e32 v41, 0x3377d1cf, v35
	v_fmac_f32_e32 v41, 0x3f317217, v35
	v_cmp_lt_f32_e64 s[0:1], |v35|, s96
	s_nop 1
	v_cndmask_b32_e64 v35, v35, v41, s[0:1]
	v_cndmask_b32_e32 v41, 0, v167, vcc
	v_sub_f32_e32 v35, v35, v41
	v_sub_f32_e32 v35, v40, v35
	v_add_f32_e32 v40, -0.5, v35
	v_mul_f32_e32 v35, 0x3fb8aa3b, v39
	v_exp_f32_e32 v35, v35
	v_mul_f32_e32 v39, 0x3fb8aa3b, v40
	v_exp_f32_e32 v39, v39
	v_mul_f32_e32 v35, 0xbfb8aa3b, v35
	v_exp_f32_e32 v35, v35
	v_mul_f32_e32 v39, 0xbfb8aa3b, v39
	v_exp_f32_e32 v39, v39
	global_store_dwordx4 v[48:49], v[32:35], off offset:512
	global_store_dwordx4 v[48:49], v[36:39], off offset:528
	s_or_b64 exec, exec, s[34:35]
	v_cmp_gt_i32_e32 vcc, s43, v152
	s_and_saveexec_b64 s[34:35], vcc
	s_cbranch_execnz .LBB0_807

.LBB0_815:
	v_readlane_b32 s68, v239, 33
	v_lshlrev_b64 v[26:27], 2, v[154:155]
	v_readlane_b32 s70, v239, 35
	v_readlane_b32 s71, v239, 36
	v_readlane_b32 s69, v239, 34
	v_readlane_b32 s72, v239, 37
	v_lshl_add_u64 v[24:25], s[70:71], 0, v[26:27]
	s_nop 1
	v_mov_b64_e32 v[16:17], v[176:177]
	v_mov_b64_e32 v[18:19], v[178:179]
	s_nop 1
	v_mov_b64_e32 v[20:21], v[172:173]
	v_mov_b64_e32 v[22:23], v[174:175]
	v_readlane_b32 s73, v239, 38
	v_readlane_b32 s74, v239, 39
	v_readlane_b32 s75, v239, 40
	v_readlane_b32 s76, v239, 41
	v_readlane_b32 s77, v239, 42
	v_readlane_b32 s78, v239, 43
	v_readlane_b32 s79, v239, 44
	v_readlane_b32 s80, v239, 45
	v_readlane_b32 s81, v239, 46
	v_readlane_b32 s82, v239, 47
	v_readlane_b32 s83, v239, 48
	v_add_f32_e32 v8, v8, v16
	v_add_f32_e32 v12, v12, v20
	v_min_f32_e32 v16, 0, v12
	v_mul_f32_e64 v12, |v12|, s49
	v_exp_f32_e32 v12, v12
	v_add_f32_e32 v13, v13, v21
	v_add_f32_e32 v9, v9, v17
	v_add_f32_e32 v14, v14, v22
	v_add_f32_e32 v12, 1.0, v12
	v_cmp_gt_f32_e32 vcc, s90, v12
	v_add_f32_e32 v10, v10, v18
	v_add_f32_e32 v15, v15, v23
	v_cndmask_b32_e64 v20, 0, 32, vcc
	v_ldexp_f32 v12, v12, v20
	v_log_f32_e32 v12, v12
	v_add_f32_e32 v11, v11, v19
	v_mul_f32_e32 v20, 0x3f317217, v12
	v_fma_f32 v20, v12, s91, -v20
	v_fmac_f32_e32 v20, 0x3377d1cf, v12
	v_fmac_f32_e32 v20, 0x3f317217, v12
	v_cmp_lt_f32_e64 s[0:1], |v12|, s96
	s_nop 1
	v_cndmask_b32_e64 v12, v12, v20, s[0:1]
	v_cndmask_b32_e32 v20, 0, v167, vcc
	v_sub_f32_e32 v12, v12, v20
	v_sub_f32_e32 v12, v16, v12
	v_min_f32_e32 v16, 0, v8
	v_mul_f32_e64 v8, |v8|, s49
	v_exp_f32_e32 v8, v8
	v_add_f32_e32 v12, -0.5, v12
	v_mul_f32_e32 v12, 0x3fb8aa3b, v12
	v_exp_f32_e32 v12, v12
	v_add_f32_e32 v8, 1.0, v8
	v_cmp_gt_f32_e32 vcc, s90, v8
	v_mul_f32_e32 v12, 0xbfb8aa3b, v12
	s_nop 0
	v_cndmask_b32_e64 v20, 0, 32, vcc
	v_ldexp_f32 v8, v8, v20
	v_log_f32_e32 v8, v8
	v_exp_f32_e32 v12, v12
	v_mul_f32_e32 v20, 0x3f317217, v8
	v_fma_f32 v20, v8, s91, -v20
	v_fmac_f32_e32 v20, 0x3377d1cf, v8
	v_fmac_f32_e32 v20, 0x3f317217, v8
	v_cmp_lt_f32_e64 s[0:1], |v8|, s96
	s_nop 1
	v_cndmask_b32_e64 v8, v8, v20, s[0:1]
	v_cndmask_b32_e32 v20, 0, v167, vcc
	v_sub_f32_e32 v8, v8, v20
	v_sub_f32_e32 v8, v16, v8
	v_min_f32_e32 v16, 0, v13
	v_mul_f32_e64 v13, |v13|, s49
	v_exp_f32_e32 v13, v13
	v_add_f32_e32 v8, -0.5, v8
	v_mul_f32_e32 v8, 0x3fb8aa3b, v8
	v_exp_f32_e32 v8, v8
	v_add_f32_e32 v13, 1.0, v13
	v_cmp_gt_f32_e32 vcc, s90, v13
	v_mul_f32_e32 v8, 0xbfb8aa3b, v8
	s_nop 0
	v_cndmask_b32_e64 v17, 0, 32, vcc
	v_ldexp_f32 v13, v13, v17
	v_log_f32_e32 v13, v13
	v_exp_f32_e32 v8, v8
	v_mul_f32_e32 v17, 0x3f317217, v13
	v_fma_f32 v17, v13, s91, -v17
	v_fmac_f32_e32 v17, 0x3377d1cf, v13
	v_fmac_f32_e32 v17, 0x3f317217, v13
	v_cmp_lt_f32_e64 s[0:1], |v13|, s96
	s_nop 1
	v_cndmask_b32_e64 v13, v13, v17, s[0:1]
	v_cndmask_b32_e32 v17, 0, v167, vcc
	v_sub_f32_e32 v13, v13, v17
	v_sub_f32_e32 v13, v16, v13
	v_min_f32_e32 v16, 0, v9
	v_mul_f32_e64 v9, |v9|, s49
	v_exp_f32_e32 v9, v9
	v_add_f32_e32 v13, -0.5, v13
	v_mul_f32_e32 v13, 0x3fb8aa3b, v13
	v_exp_f32_e32 v13, v13
	v_add_f32_e32 v9, 1.0, v9
	v_cmp_gt_f32_e32 vcc, s90, v9
	v_mul_f32_e32 v13, 0xbfb8aa3b, v13
	s_nop 0
	v_cndmask_b32_e64 v17, 0, 32, vcc
	v_ldexp_f32 v9, v9, v17
	v_log_f32_e32 v9, v9
	v_exp_f32_e32 v13, v13
	v_mul_f32_e32 v17, 0x3f317217, v9
	v_fma_f32 v17, v9, s91, -v17
	v_fmac_f32_e32 v17, 0x3377d1cf, v9
	v_fmac_f32_e32 v17, 0x3f317217, v9
	v_cmp_lt_f32_e64 s[0:1], |v9|, s96
	s_nop 1
	v_cndmask_b32_e64 v9, v9, v17, s[0:1]
	v_cndmask_b32_e32 v17, 0, v167, vcc
	v_sub_f32_e32 v9, v9, v17
	v_sub_f32_e32 v9, v16, v9
	v_min_f32_e32 v16, 0, v14
	v_mul_f32_e64 v14, |v14|, s49
	v_exp_f32_e32 v14, v14
	v_add_f32_e32 v9, -0.5, v9
	v_mul_f32_e32 v9, 0x3fb8aa3b, v9
	v_exp_f32_e32 v9, v9
	v_add_f32_e32 v14, 1.0, v14
	v_cmp_gt_f32_e32 vcc, s90, v14
	v_mul_f32_e32 v9, 0xbfb8aa3b, v9
	s_nop 0
	v_cndmask_b32_e64 v17, 0, 32, vcc
	v_ldexp_f32 v14, v14, v17
	v_log_f32_e32 v14, v14
	v_exp_f32_e32 v9, v9
	v_mul_f32_e32 v17, 0x3f317217, v14
	v_fma_f32 v17, v14, s91, -v17
	v_fmac_f32_e32 v17, 0x3377d1cf, v14
	v_fmac_f32_e32 v17, 0x3f317217, v14
	v_cmp_lt_f32_e64 s[0:1], |v14|, s96
	s_nop 1
	v_cndmask_b32_e64 v14, v14, v17, s[0:1]
	v_cndmask_b32_e32 v17, 0, v167, vcc
	v_sub_f32_e32 v14, v14, v17
	v_sub_f32_e32 v14, v16, v14
	v_min_f32_e32 v16, 0, v10
	v_mul_f32_e64 v10, |v10|, s49
	v_exp_f32_e32 v10, v10
	v_add_f32_e32 v14, -0.5, v14
	v_mul_f32_e32 v14, 0x3fb8aa3b, v14
	v_exp_f32_e32 v14, v14
	v_add_f32_e32 v10, 1.0, v10
	v_cmp_gt_f32_e32 vcc, s90, v10
	v_mul_f32_e32 v14, 0xbfb8aa3b, v14
	s_nop 0
	v_cndmask_b32_e64 v17, 0, 32, vcc
	v_ldexp_f32 v10, v10, v17
	v_log_f32_e32 v10, v10
	v_exp_f32_e32 v14, v14
	v_mul_f32_e32 v17, 0x3f317217, v10
	v_fma_f32 v17, v10, s91, -v17
	v_fmac_f32_e32 v17, 0x3377d1cf, v10
	v_fmac_f32_e32 v17, 0x3f317217, v10
	v_cmp_lt_f32_e64 s[0:1], |v10|, s96
	s_nop 1
	v_cndmask_b32_e64 v10, v10, v17, s[0:1]
	v_cndmask_b32_e32 v17, 0, v167, vcc
	v_sub_f32_e32 v10, v10, v17
	v_sub_f32_e32 v10, v16, v10
	v_min_f32_e32 v16, 0, v15
	v_mul_f32_e64 v15, |v15|, s49
	v_exp_f32_e32 v15, v15
	v_add_f32_e32 v10, -0.5, v10
	v_mul_f32_e32 v10, 0x3fb8aa3b, v10
	v_exp_f32_e32 v10, v10
	v_add_f32_e32 v15, 1.0, v15
	v_cmp_gt_f32_e32 vcc, s90, v15
	v_mul_f32_e32 v10, 0xbfb8aa3b, v10
	s_nop 0
	v_cndmask_b32_e64 v17, 0, 32, vcc
	v_ldexp_f32 v15, v15, v17
	v_log_f32_e32 v15, v15
	v_exp_f32_e32 v10, v10
	v_mul_f32_e32 v17, 0x3f317217, v15
	v_fma_f32 v17, v15, s91, -v17
	v_fmac_f32_e32 v17, 0x3377d1cf, v15
	v_fmac_f32_e32 v17, 0x3f317217, v15
	v_cmp_lt_f32_e64 s[0:1], |v15|, s96
	s_nop 1
	v_cndmask_b32_e64 v15, v15, v17, s[0:1]
	v_cndmask_b32_e32 v17, 0, v167, vcc
	v_sub_f32_e32 v15, v15, v17
	v_sub_f32_e32 v15, v16, v15
	v_min_f32_e32 v16, 0, v11
	v_mul_f32_e64 v11, |v11|, s49
	v_exp_f32_e32 v11, v11
	v_add_f32_e32 v15, -0.5, v15
	v_mul_f32_e32 v15, 0x3fb8aa3b, v15
	v_exp_f32_e32 v15, v15
	v_add_f32_e32 v11, 1.0, v11
	v_cmp_gt_f32_e32 vcc, s90, v11
	v_mul_f32_e32 v15, 0xbfb8aa3b, v15
	s_nop 0
	v_cndmask_b32_e64 v17, 0, 32, vcc
	v_ldexp_f32 v11, v11, v17
	v_log_f32_e32 v11, v11
	v_exp_f32_e32 v15, v15
	v_mul_f32_e32 v17, 0x3f317217, v11
	v_fma_f32 v17, v11, s91, -v17
	v_fmac_f32_e32 v17, 0x3377d1cf, v11
	v_fmac_f32_e32 v17, 0x3f317217, v11
	v_cmp_lt_f32_e64 s[0:1], |v11|, s96
	s_nop 1
	v_cndmask_b32_e64 v11, v11, v17, s[0:1]
	v_cndmask_b32_e32 v17, 0, v167, vcc
	v_sub_f32_e32 v11, v11, v17
	v_sub_f32_e32 v11, v16, v11
	v_add_f32_e32 v11, -0.5, v11
	v_mul_f32_e32 v11, 0x3fb8aa3b, v11
	v_exp_f32_e32 v11, v11
	v_lshlrev_b64 v[16:17], 12, v[152:153]
	v_lshl_add_u64 v[16:17], s[10:11], 0, v[16:17]
	v_lshl_add_u64 v[18:19], v[16:17], 0, v[26:27]
	v_mul_f32_e32 v11, 0xbfb8aa3b, v11
	s_mov_b64 s[0:1], 0xb0000
	v_exp_f32_e32 v11, v11
	v_lshl_add_u64 v[16:17], v[18:19], 0, s[0:1]
	s_mov_b32 s0, 0xb0000
	v_add_co_u32_e32 v18, vcc, s0, v18
	s_nop 1
	v_addc_co_u32_e32 v19, vcc, 0, v19, vcc
	global_store_dwordx4 v[18:19], v[12:15], off
	global_store_dwordx4 v[16:17], v[8:11], off offset:16
	s_nop 1
	v_mov_b64_e32 v[8:9], v[184:185]
	v_mov_b64_e32 v[10:11], v[186:187]
	s_nop 0
	s_nop 1
	v_mov_b64_e32 v[12:13], v[180:181]
	v_mov_b64_e32 v[14:15], v[182:183]
	v_add_f32_e32 v0, v0, v8
	v_add_f32_e32 v4, v4, v12
	v_min_f32_e32 v8, 0, v4
	v_mul_f32_e64 v4, |v4|, s49
	v_exp_f32_e32 v4, v4
	v_add_f32_e32 v5, v5, v13
	v_add_f32_e32 v1, v1, v9
	v_add_f32_e32 v6, v6, v14
	v_add_f32_e32 v4, 1.0, v4
	v_cmp_gt_f32_e32 vcc, s90, v4
	v_add_f32_e32 v2, v2, v10
	v_add_f32_e32 v7, v7, v15
	v_cndmask_b32_e64 v12, 0, 32, vcc
	v_ldexp_f32 v4, v4, v12
	v_log_f32_e32 v4, v4
	v_add_f32_e32 v3, v3, v11
	v_mul_f32_e32 v12, 0x3f317217, v4
	v_fma_f32 v12, v4, s91, -v12
	v_fmac_f32_e32 v12, 0x3377d1cf, v4
	v_fmac_f32_e32 v12, 0x3f317217, v4
	v_cmp_lt_f32_e64 s[0:1], |v4|, s96
	s_nop 1
	v_cndmask_b32_e64 v4, v4, v12, s[0:1]
	v_cndmask_b32_e32 v12, 0, v167, vcc
	v_sub_f32_e32 v4, v4, v12
	v_sub_f32_e32 v4, v8, v4
	v_min_f32_e32 v8, 0, v0
	v_mul_f32_e64 v0, |v0|, s49
	v_exp_f32_e32 v0, v0
	v_add_f32_e32 v4, -0.5, v4
	v_add_f32_e32 v0, 1.0, v0
	v_cmp_gt_f32_e32 vcc, s90, v0
	s_nop 1
	v_cndmask_b32_e64 v12, 0, 32, vcc
	v_ldexp_f32 v0, v0, v12
	v_log_f32_e32 v0, v0
	s_nop 0
	v_mul_f32_e32 v12, 0x3f317217, v0
	v_fma_f32 v12, v0, s91, -v12
	v_fmac_f32_e32 v12, 0x3377d1cf, v0
	v_fmac_f32_e32 v12, 0x3f317217, v0
	v_cmp_lt_f32_e64 s[0:1], |v0|, s96
	s_nop 1
	v_cndmask_b32_e64 v0, v0, v12, s[0:1]
	v_cndmask_b32_e32 v12, 0, v167, vcc
	v_sub_f32_e32 v0, v0, v12
	v_sub_f32_e32 v0, v8, v0
	v_add_f32_e32 v8, -0.5, v0
	v_mul_f32_e32 v0, 0x3fb8aa3b, v4
	v_mul_f32_e32 v4, 0x3fb8aa3b, v8
	v_min_f32_e32 v8, 0, v5
	v_mul_f32_e64 v5, |v5|, s49
	v_exp_f32_e32 v5, v5
	v_exp_f32_e32 v0, v0
	v_exp_f32_e32 v4, v4
	v_add_f32_e32 v5, 1.0, v5
	v_cmp_gt_f32_e32 vcc, s90, v5
	v_mul_f32_e32 v0, 0xbfb8aa3b, v0
	v_exp_f32_e32 v0, v0
	v_cndmask_b32_e64 v9, 0, 32, vcc
	v_ldexp_f32 v5, v5, v9
	v_log_f32_e32 v5, v5
	v_mul_f32_e32 v4, 0xbfb8aa3b, v4
	v_exp_f32_e32 v4, v4
	v_mul_f32_e32 v9, 0x3f317217, v5
	v_fma_f32 v9, v5, s91, -v9
	v_fmac_f32_e32 v9, 0x3377d1cf, v5
	v_fmac_f32_e32 v9, 0x3f317217, v5
	v_cmp_lt_f32_e64 s[0:1], |v5|, s96
	s_nop 1
	v_cndmask_b32_e64 v5, v5, v9, s[0:1]
	v_cndmask_b32_e32 v9, 0, v167, vcc
	v_sub_f32_e32 v5, v5, v9
	v_sub_f32_e32 v5, v8, v5
	v_min_f32_e32 v8, 0, v1
	v_mul_f32_e64 v1, |v1|, s49
	v_exp_f32_e32 v1, v1
	v_add_f32_e32 v5, -0.5, v5
	v_add_f32_e32 v1, 1.0, v1
	v_cmp_gt_f32_e32 vcc, s90, v1
	s_nop 1
	v_cndmask_b32_e64 v9, 0, 32, vcc
	v_ldexp_f32 v1, v1, v9
	v_log_f32_e32 v1, v1
	s_nop 0
	v_mul_f32_e32 v9, 0x3f317217, v1
	v_fma_f32 v9, v1, s91, -v9
	v_fmac_f32_e32 v9, 0x3377d1cf, v1
	v_fmac_f32_e32 v9, 0x3f317217, v1
	v_cmp_lt_f32_e64 s[0:1], |v1|, s96
	s_nop 1
	v_cndmask_b32_e64 v1, v1, v9, s[0:1]
	v_cndmask_b32_e32 v9, 0, v167, vcc
	v_sub_f32_e32 v1, v1, v9
	v_sub_f32_e32 v1, v8, v1
	v_add_f32_e32 v8, -0.5, v1
	v_mul_f32_e32 v1, 0x3fb8aa3b, v5
	v_mul_f32_e32 v5, 0x3fb8aa3b, v8
	v_min_f32_e32 v8, 0, v6
	v_mul_f32_e64 v6, |v6|, s49
	v_exp_f32_e32 v6, v6
	v_exp_f32_e32 v1, v1
	v_exp_f32_e32 v5, v5
	v_add_f32_e32 v6, 1.0, v6
	v_cmp_gt_f32_e32 vcc, s90, v6
	v_mul_f32_e32 v1, 0xbfb8aa3b, v1
	v_exp_f32_e32 v1, v1
	v_cndmask_b32_e64 v9, 0, 32, vcc
	v_ldexp_f32 v6, v6, v9
	v_log_f32_e32 v6, v6
	v_mul_f32_e32 v5, 0xbfb8aa3b, v5
	v_exp_f32_e32 v5, v5
	v_mul_f32_e32 v9, 0x3f317217, v6
	v_fma_f32 v9, v6, s91, -v9
	v_fmac_f32_e32 v9, 0x3377d1cf, v6
	v_fmac_f32_e32 v9, 0x3f317217, v6
	v_cmp_lt_f32_e64 s[0:1], |v6|, s96
	s_nop 1
	v_cndmask_b32_e64 v6, v6, v9, s[0:1]
	v_cndmask_b32_e32 v9, 0, v167, vcc
	v_sub_f32_e32 v6, v6, v9
	v_sub_f32_e32 v6, v8, v6
	v_min_f32_e32 v8, 0, v2
	v_mul_f32_e64 v2, |v2|, s49
	v_exp_f32_e32 v2, v2
	v_add_f32_e32 v6, -0.5, v6
	v_add_f32_e32 v2, 1.0, v2
	v_cmp_gt_f32_e32 vcc, s90, v2
	s_nop 1
	v_cndmask_b32_e64 v9, 0, 32, vcc
	v_ldexp_f32 v2, v2, v9
	v_log_f32_e32 v2, v2
	s_nop 0
	v_mul_f32_e32 v9, 0x3f317217, v2
	v_fma_f32 v9, v2, s91, -v9
	v_fmac_f32_e32 v9, 0x3377d1cf, v2
	v_fmac_f32_e32 v9, 0x3f317217, v2
	v_cmp_lt_f32_e64 s[0:1], |v2|, s96
	s_nop 1
	v_cndmask_b32_e64 v2, v2, v9, s[0:1]
	v_cndmask_b32_e32 v9, 0, v167, vcc
	v_sub_f32_e32 v2, v2, v9
	v_sub_f32_e32 v2, v8, v2
	v_add_f32_e32 v8, -0.5, v2
	v_mul_f32_e32 v2, 0x3fb8aa3b, v6
	v_mul_f32_e32 v6, 0x3fb8aa3b, v8
	v_min_f32_e32 v8, 0, v7
	v_mul_f32_e64 v7, |v7|, s49
	v_exp_f32_e32 v7, v7
	v_exp_f32_e32 v2, v2
	v_exp_f32_e32 v6, v6
	v_add_f32_e32 v7, 1.0, v7
	v_cmp_gt_f32_e32 vcc, s90, v7
	v_mul_f32_e32 v2, 0xbfb8aa3b, v2
	v_exp_f32_e32 v2, v2
	v_cndmask_b32_e64 v9, 0, 32, vcc
	v_ldexp_f32 v7, v7, v9
	v_log_f32_e32 v7, v7
	v_mul_f32_e32 v6, 0xbfb8aa3b, v6
	v_exp_f32_e32 v6, v6
	v_mul_f32_e32 v9, 0x3f317217, v7
	v_fma_f32 v9, v7, s91, -v9
	v_fmac_f32_e32 v9, 0x3377d1cf, v7
	v_fmac_f32_e32 v9, 0x3f317217, v7
	v_cmp_lt_f32_e64 s[0:1], |v7|, s96
	s_nop 1
	v_cndmask_b32_e64 v7, v7, v9, s[0:1]
	v_cndmask_b32_e32 v9, 0, v167, vcc
	v_sub_f32_e32 v7, v7, v9
	v_sub_f32_e32 v7, v8, v7
	v_min_f32_e32 v8, 0, v3
	v_mul_f32_e64 v3, |v3|, s49
	v_exp_f32_e32 v3, v3
	v_add_f32_e32 v7, -0.5, v7
	v_add_f32_e32 v3, 1.0, v3
	v_cmp_gt_f32_e32 vcc, s90, v3
	s_nop 1
	v_cndmask_b32_e64 v9, 0, 32, vcc
	v_ldexp_f32 v3, v3, v9
	v_log_f32_e32 v3, v3
	s_nop 0
	v_mul_f32_e32 v9, 0x3f317217, v3
	v_fma_f32 v9, v3, s91, -v9
	v_fmac_f32_e32 v9, 0x3377d1cf, v3
	v_fmac_f32_e32 v9, 0x3f317217, v3
	v_cmp_lt_f32_e64 s[0:1], |v3|, s96
	s_nop 1
	v_cndmask_b32_e64 v3, v3, v9, s[0:1]
	v_cndmask_b32_e32 v9, 0, v167, vcc
	v_sub_f32_e32 v3, v3, v9
	v_sub_f32_e32 v3, v8, v3
	v_add_f32_e32 v8, -0.5, v3
	v_mul_f32_e32 v3, 0x3fb8aa3b, v7
	v_exp_f32_e32 v3, v3
	v_mul_f32_e32 v7, 0x3fb8aa3b, v8
	v_exp_f32_e32 v7, v7
	v_mul_f32_e32 v3, 0xbfb8aa3b, v3
	v_exp_f32_e32 v3, v3
	v_mul_f32_e32 v7, 0xbfb8aa3b, v7
	v_exp_f32_e32 v7, v7
	global_store_dwordx4 v[16:17], v[0:3], off offset:512
	global_store_dwordx4 v[16:17], v[4:7], off offset:528
